# LDS XOR swizzle of the rg LA/LI arrays also in phase 4 (rg_phase<true>: gate stores, element-wise pass, scan reads and writes, output reads)
# speedup vs baseline: 1.0106x; 1.0106x over previous
.LBB0_609:
	s_waitcnt vmcnt(0)
	v_cmp_gt_u32_e64 s[98:99], s49, v204
	v_mul_f32_e32 v240, 0xc1000000, v88
	v_mul_f32_e32 v241, 0xc1000000, v89
	v_mul_f32_e32 v242, 0xc1000000, v90
	v_mul_f32_e32 v243, 0xc1000000, v91
	v_mul_f32_e32 v244, 0xc1000000, v92
	v_mul_f32_e32 v245, 0xc1000000, v93
	v_mul_f32_e32 v246, 0xc1000000, v94
	v_mul_f32_e32 v247, 0xc1000000, v95
	v_cndmask_b32_e64 v240, 1.0, v240, s[98:99]
	v_cndmask_b32_e64 v241, 1.0, v241, s[98:99]
	v_cndmask_b32_e64 v242, 1.0, v242, s[98:99]
	v_cndmask_b32_e64 v243, 1.0, v243, s[98:99]
	v_cndmask_b32_e64 v244, 1.0, v244, s[98:99]
	v_cndmask_b32_e64 v245, 1.0, v245, s[98:99]
	v_cndmask_b32_e64 v246, 1.0, v246, s[98:99]
	v_cndmask_b32_e64 v247, 1.0, v247, s[98:99]
	v_and_b32_e32 v192, 63, v204
	v_bfe_u32 v193, v204, 6, 1
	v_lshl_or_b32 v192, v193, 12, v192
	v_mul_u32_u24_e32 v193, 63, v193
	v_lshrrev_b32_e32 v194, 7, v204
	v_lshlrev_b32_e32 v194, 4, v194
	v_or_b32_e32 v176, 0, v194
	v_xor_b32_e32 v176, v193, v176
	v_and_b32_e32 v195, 3, v176
	v_lshlrev_b32_e32 v195, 4, v195
	v_lshl_add_u32 v176, v176, 6, v192
	v_lshlrev_b32_e32 v176, 2, v176
	v_xor_b32_e32 v176, v195, v176
	v_or_b32_e32 v177, 1, v194
	v_xor_b32_e32 v177, v193, v177
	v_and_b32_e32 v195, 3, v177
	v_lshlrev_b32_e32 v195, 4, v195
	v_lshl_add_u32 v177, v177, 6, v192
	v_lshlrev_b32_e32 v177, 2, v177
	v_xor_b32_e32 v177, v195, v177
	v_or_b32_e32 v178, 2, v194
	v_xor_b32_e32 v178, v193, v178
	v_and_b32_e32 v195, 3, v178
	v_lshlrev_b32_e32 v195, 4, v195
	v_lshl_add_u32 v178, v178, 6, v192
	v_lshlrev_b32_e32 v178, 2, v178
	v_xor_b32_e32 v178, v195, v178
	v_or_b32_e32 v179, 3, v194
	v_xor_b32_e32 v179, v193, v179
	v_and_b32_e32 v195, 3, v179
	v_lshlrev_b32_e32 v195, 4, v195
	v_lshl_add_u32 v179, v179, 6, v192
	v_lshlrev_b32_e32 v179, 2, v179
	v_xor_b32_e32 v179, v195, v179
	v_or_b32_e32 v180, 4, v194
	v_xor_b32_e32 v180, v193, v180
	v_and_b32_e32 v195, 3, v180
	v_lshlrev_b32_e32 v195, 4, v195
	v_lshl_add_u32 v180, v180, 6, v192
	v_lshlrev_b32_e32 v180, 2, v180
	v_xor_b32_e32 v180, v195, v180
	v_or_b32_e32 v181, 5, v194
	v_xor_b32_e32 v181, v193, v181
	v_and_b32_e32 v195, 3, v181
	v_lshlrev_b32_e32 v195, 4, v195
	v_lshl_add_u32 v181, v181, 6, v192
	v_lshlrev_b32_e32 v181, 2, v181
	v_xor_b32_e32 v181, v195, v181
	v_or_b32_e32 v182, 6, v194
	v_xor_b32_e32 v182, v193, v182
	v_and_b32_e32 v195, 3, v182
	v_lshlrev_b32_e32 v195, 4, v195
	v_lshl_add_u32 v182, v182, 6, v192
	v_lshlrev_b32_e32 v182, 2, v182
	v_xor_b32_e32 v182, v195, v182
	v_or_b32_e32 v183, 7, v194
	v_xor_b32_e32 v183, v193, v183
	v_and_b32_e32 v195, 3, v183
	v_lshlrev_b32_e32 v195, 4, v195
	v_lshl_add_u32 v183, v183, 6, v192
	v_lshlrev_b32_e32 v183, 2, v183
	v_xor_b32_e32 v183, v195, v183
	v_or_b32_e32 v184, 8, v194
	v_xor_b32_e32 v184, v193, v184
	v_and_b32_e32 v195, 3, v184
	v_lshlrev_b32_e32 v195, 4, v195
	v_lshl_add_u32 v184, v184, 6, v192
	v_lshlrev_b32_e32 v184, 2, v184
	v_xor_b32_e32 v184, v195, v184
	v_or_b32_e32 v185, 9, v194
	v_xor_b32_e32 v185, v193, v185
	v_and_b32_e32 v195, 3, v185
	v_lshlrev_b32_e32 v195, 4, v195
	v_lshl_add_u32 v185, v185, 6, v192
	v_lshlrev_b32_e32 v185, 2, v185
	v_xor_b32_e32 v185, v195, v185
	v_or_b32_e32 v186, 10, v194
	v_xor_b32_e32 v186, v193, v186
	v_and_b32_e32 v195, 3, v186
	v_lshlrev_b32_e32 v195, 4, v195
	v_lshl_add_u32 v186, v186, 6, v192
	v_lshlrev_b32_e32 v186, 2, v186
	v_xor_b32_e32 v186, v195, v186
	v_or_b32_e32 v187, 11, v194
	v_xor_b32_e32 v187, v193, v187
	v_and_b32_e32 v195, 3, v187
	v_lshlrev_b32_e32 v195, 4, v195
	v_lshl_add_u32 v187, v187, 6, v192
	v_lshlrev_b32_e32 v187, 2, v187
	v_xor_b32_e32 v187, v195, v187
	v_or_b32_e32 v188, 12, v194
	v_xor_b32_e32 v188, v193, v188
	v_and_b32_e32 v195, 3, v188
	v_lshlrev_b32_e32 v195, 4, v195
	v_lshl_add_u32 v188, v188, 6, v192
	v_lshlrev_b32_e32 v188, 2, v188
	v_xor_b32_e32 v188, v195, v188
	v_or_b32_e32 v189, 13, v194
	v_xor_b32_e32 v189, v193, v189
	v_and_b32_e32 v195, 3, v189
	v_lshlrev_b32_e32 v195, 4, v195
	v_lshl_add_u32 v189, v189, 6, v192
	v_lshlrev_b32_e32 v189, 2, v189
	v_xor_b32_e32 v189, v195, v189
	v_or_b32_e32 v190, 14, v194
	v_xor_b32_e32 v190, v193, v190
	v_and_b32_e32 v195, 3, v190
	v_lshlrev_b32_e32 v195, 4, v195
	v_lshl_add_u32 v190, v190, 6, v192
	v_lshlrev_b32_e32 v190, 2, v190
	v_xor_b32_e32 v190, v195, v190
	v_or_b32_e32 v191, 15, v194
	v_xor_b32_e32 v191, v193, v191
	v_and_b32_e32 v195, 3, v191
	v_lshlrev_b32_e32 v195, 4, v195
	v_lshl_add_u32 v191, v191, 6, v192
	v_lshlrev_b32_e32 v191, 2, v191
	v_xor_b32_e32 v191, v195, v191
	v_and_b32_e32 v200, 0x30, v204
	v_and_b32_e32 v201, 3, v204
	v_lshlrev_b32_e32 v201, 4, v201
	v_mov_b32_e32 v2, v0
	v_mov_b32_e32 v3, v0
	v_mov_b32_e32 v1, v0
	v_mov_b32_e32 v68, 0
	v_mov_b64_e32 v[114:115], v[2:3]
	v_mov_b32_e32 v150, 0
	v_readlane_b32 s12, v238, 15
	s_mov_b32 s13, s3
	s_mov_b32 s2, s97
	v_mov_b64_e32 v[112:113], v[0:1]
	v_mov_b32_e32 v69, v68
	v_mov_b32_e32 v70, v68
	v_mov_b32_e32 v71, v68
	v_mov_b32_e32 v96, v68
	v_mov_b32_e32 v97, v68
	v_mov_b32_e32 v98, v68
	v_mov_b32_e32 v99, v68
	v_mov_b32_e32 v104, v68
	v_mov_b32_e32 v105, v68
	v_mov_b32_e32 v106, v68
	v_mov_b32_e32 v107, v68
	v_mov_b32_e32 v108, v68
	v_mov_b32_e32 v109, v68
	v_mov_b32_e32 v110, v68
	v_mov_b32_e32 v111, v68
	s_branch .LBB0_612
.LBB0_610:
	s_or_b64 exec, exec, s[6:7]
	v_lshlrev_b32_e32 v153, 14, v153
	v_lshlrev_b32_e32 v154, 2, v154
	v_add3_u32 v153, 0, v153, v154
	v_fmac_f32_e32 v117, v116, v152
	v_lshl_add_u32 v116, v155, 8, v153
	ds_write_b32 v176, v117 offset:58368
	v_fmac_f32_e32 v119, v118, v117
	v_lshl_add_u32 v116, v157, 8, v153
	ds_write_b32 v177, v119 offset:58368
	v_fmac_f32_e32 v121, v120, v119
	v_lshl_add_u32 v116, v158, 8, v153
	ds_write_b32 v178, v121 offset:58368
	v_fmac_f32_e32 v123, v122, v121
	v_lshl_add_u32 v116, v159, 8, v153
	ds_write_b32 v179, v123 offset:58368
	v_fmac_f32_e32 v125, v124, v123
	v_lshl_add_u32 v116, v160, 8, v153
	ds_write_b32 v180, v125 offset:58368
	v_fmac_f32_e32 v127, v126, v125
	v_lshl_add_u32 v116, v161, 8, v153
	ds_write_b32 v181, v127 offset:58368
	v_fmac_f32_e32 v129, v128, v127
	v_lshl_add_u32 v116, v162, 8, v153
	ds_write_b32 v182, v129 offset:58368
	v_fmac_f32_e32 v131, v130, v129
	v_lshl_add_u32 v116, v163, 8, v153
	ds_write_b32 v183, v131 offset:58368
	v_fmac_f32_e32 v133, v132, v131
	v_lshl_add_u32 v116, v164, 8, v153
	ds_write_b32 v184, v133 offset:58368
	v_fmac_f32_e32 v135, v134, v133
	v_lshl_add_u32 v116, v165, 8, v153
	ds_write_b32 v185, v135 offset:58368
	v_fmac_f32_e32 v137, v136, v135
	v_lshl_add_u32 v116, v166, 8, v153
	ds_write_b32 v186, v137 offset:58368
	v_fmac_f32_e32 v139, v138, v137
	v_lshl_add_u32 v116, v167, 8, v153
	ds_write_b32 v187, v139 offset:58368
	v_fmac_f32_e32 v141, v140, v139
	v_lshl_add_u32 v116, v168, 8, v153
	ds_write_b32 v188, v141 offset:58368
	v_fmac_f32_e32 v143, v142, v141
	v_lshl_add_u32 v116, v169, 8, v153
	ds_write_b32 v189, v143 offset:58368
	v_fmac_f32_e32 v145, v144, v143
	v_lshl_add_u32 v116, v170, 8, v153
	ds_write_b32 v190, v145 offset:58368
	v_fmac_f32_e32 v147, v146, v145
	v_lshl_add_u32 v116, v171, 8, v153
	v_lshlrev_b32_e32 v132, 16, v112
	ds_write_b32 v191, v147 offset:58368
	v_mul_f32_e32 v116, 0x3d372713, v132
	v_mul_f32_e32 v116, v116, v132
	v_mov_b32_e32 v117, v132
	v_fmac_f32_e32 v117, v116, v117
	v_mul_f32_e32 v116, 0x3f4c422a, v117
	v_lshlrev_b32_e32 v117, 2, v1
	v_and_b32_e32 v133, 0xffff0000, v112
	v_add3_u32 v128, v151, v117, s46
	v_mul_f32_e32 v117, 0x3d372713, v133
	v_mul_f32_e32 v117, v117, v133
	v_mov_b32_e32 v118, v133
	v_fmac_f32_e32 v118, v117, v118
	v_add_f32_e32 v116, v116, v116
	v_mul_f32_e32 v117, 0x3f4c422a, v118
	v_mul_f32_e32 v116, 0x3fb8aa3b, v116
	v_add_f32_e32 v117, v117, v117
	v_exp_f32_e32 v116, v116
	v_mul_f32_e32 v117, 0x3fb8aa3b, v117
	v_exp_f32_e32 v124, v117
	s_waitcnt lgkmcnt(0)
	v_add_f32_e32 v116, 1.0, v116
	s_barrier
	v_lshlrev_b32_e32 v196, 1, v204
	v_and_b32_e32 v196, 0x30, v196
	v_xor_b32_e32 v197, v196, v3
	v_xor_b32_e32 v198, 16, v197
	v_xor_b32_e32 v199, v196, v128
	v_xor_b32_e32 v202, 16, v199
	v_rcp_f32_e32 v134, v116
	ds_read_b128 v[116:119], v197 offset:58368
	ds_read_b128 v[120:123], v199 offset:16384
	v_add_f32_e32 v124, 1.0, v124
	v_rcp_f32_e32 v135, v124
	ds_read_b128 v[124:127], v198 offset:58368
	ds_read_b128 v[128:131], v202 offset:16384
	v_pk_mul_f32 v[132:133], v[132:133], 0.5 op_sel_hi:[1,0]
	s_waitcnt lgkmcnt(2)
	v_pk_add_f32 v[116:117], v[116:117], v[120:121]
	v_pk_fma_f32 v[120:121], v[134:135], 2.0, 1.0 op_sel_hi:[1,0,0] neg_lo:[1,0,0] neg_hi:[1,0,0]
	v_lshlrev_b32_e32 v134, 16, v113
	v_mul_f32_e32 v3, 0x3d372713, v134
	v_mul_f32_e32 v3, v3, v134
	v_mov_b32_e32 v136, v134
	v_and_b32_e32 v135, 0xffff0000, v113
	v_fmac_f32_e32 v136, v3, v136
	v_mul_f32_e32 v3, 0x3f4c422a, v136
	v_mul_f32_e32 v136, 0x3d372713, v135
	v_mul_f32_e32 v136, v136, v135
	v_mov_b32_e32 v137, v135
	v_fmac_f32_e32 v137, v136, v137
	v_add_f32_e32 v3, v3, v3
	v_mul_f32_e32 v136, 0x3f4c422a, v137
	v_mul_f32_e32 v3, 0x3fb8aa3b, v3
	v_add_f32_e32 v136, v136, v136
	v_exp_f32_e32 v3, v3
	v_mul_f32_e32 v136, 0x3fb8aa3b, v136
	v_exp_f32_e32 v137, v136
	v_pk_add_f32 v[120:121], v[120:121], 1.0 op_sel_hi:[1,0]
	v_add_f32_e32 v3, 1.0, v3
	v_rcp_f32_e32 v136, v3
	v_add_f32_e32 v3, 1.0, v137
	v_pk_mul_f32 v[120:121], v[132:133], v[120:121]
	v_lshlrev_b32_e32 v132, 16, v114
	v_rcp_f32_e32 v137, v3
	v_mul_f32_e32 v3, 0x3d372713, v132
	v_pk_add_f32 v[118:119], v[118:119], v[122:123]
	v_pk_mul_f32 v[122:123], v[134:135], 0.5 op_sel_hi:[1,0]
	v_mul_f32_e32 v3, v3, v132
	v_mov_b32_e32 v134, v132
	v_and_b32_e32 v133, 0xffff0000, v114
	v_fmac_f32_e32 v134, v3, v134
	v_mul_f32_e32 v3, 0x3f4c422a, v134
	v_mul_f32_e32 v134, 0x3d372713, v133
	v_mul_f32_e32 v134, v134, v133
	v_mov_b32_e32 v135, v133
	v_fmac_f32_e32 v135, v134, v135
	v_add_f32_e32 v3, v3, v3
	v_mul_f32_e32 v134, 0x3f4c422a, v135
	v_mul_f32_e32 v3, 0x3fb8aa3b, v3
	v_add_f32_e32 v134, v134, v134
	v_exp_f32_e32 v3, v3
	v_mul_f32_e32 v134, 0x3fb8aa3b, v134
	v_exp_f32_e32 v135, v134
	v_pk_mul_f32 v[116:117], v[120:121], v[116:117]
	v_pk_fma_f32 v[120:121], v[136:137], 2.0, 1.0 op_sel_hi:[1,0,0] neg_lo:[1,0,0] neg_hi:[1,0,0]
	v_add_f32_e32 v3, 1.0, v3
	v_pk_add_f32 v[120:121], v[120:121], 1.0 op_sel_hi:[1,0]
	v_rcp_f32_e32 v134, v3
	v_pk_mul_f32 v[120:121], v[122:123], v[120:121]
	v_add_f32_e32 v3, 1.0, v135
	v_pk_mul_f32 v[118:119], v[120:121], v[118:119]
	s_waitcnt lgkmcnt(0)
	v_pk_add_f32 v[120:121], v[124:125], v[128:129]
	v_lshlrev_b32_e32 v128, 16, v115
	v_rcp_f32_e32 v135, v3
	v_mul_f32_e32 v3, 0x3d372713, v128
	v_pk_mul_f32 v[124:125], v[132:133], 0.5 op_sel_hi:[1,0]
	v_mul_f32_e32 v3, v3, v128
	v_mov_b32_e32 v132, v128
	v_and_b32_e32 v129, 0xffff0000, v115
	v_fmac_f32_e32 v132, v3, v132
	v_mul_f32_e32 v3, 0x3f4c422a, v132
	v_mul_f32_e32 v132, 0x3d372713, v129
	v_mul_f32_e32 v132, v132, v129
	v_mov_b32_e32 v133, v129
	v_fmac_f32_e32 v133, v132, v133
	v_add_f32_e32 v3, v3, v3
	v_mul_f32_e32 v132, 0x3f4c422a, v133
	v_mul_f32_e32 v3, 0x3fb8aa3b, v3
	v_add_f32_e32 v132, v132, v132
	v_exp_f32_e32 v3, v3
	v_mul_f32_e32 v132, 0x3fb8aa3b, v132
	v_exp_f32_e32 v133, v132
	s_ashr_i32 s6, s50, 9
	v_add_f32_e32 v3, 1.0, v3
	v_rcp_f32_e32 v132, v3
	v_add_f32_e32 v3, 1.0, v133
	v_rcp_f32_e32 v133, v3
	s_ashr_i32 s7, s6, 31
	s_add_i32 s8, s83, s12
	v_pk_fma_f32 v[122:123], v[134:135], 2.0, 1.0 op_sel_hi:[1,0,0] neg_lo:[1,0,0] neg_hi:[1,0,0]
	s_lshl_b64 s[6:7], s[6:7], 12
	s_and_b32 s8, s8, 0xfc0
	v_pk_add_f32 v[122:123], v[122:123], 1.0 op_sel_hi:[1,0]
	s_or_b32 s6, s6, s8
	v_ashrrev_i32_e32 v3, 31, v2
	v_pk_mul_f32 v[122:123], v[124:125], v[122:123]
	v_pk_fma_f32 v[124:125], v[132:133], 2.0, 1.0 op_sel_hi:[1,0,0] neg_lo:[1,0,0] neg_hi:[1,0,0]
	v_lshl_add_u64 v[2:3], s[6:7], 0, v[2:3]
	s_add_i32 s6, s90, s13
	v_pk_mul_f32 v[120:121], v[122:123], v[120:121]
	v_pk_add_f32 v[122:123], v[126:127], v[130:131]
	v_pk_mul_f32 v[126:127], v[128:129], 0.5 op_sel_hi:[1,0]
	v_pk_add_f32 v[124:125], v[124:125], 1.0 op_sel_hi:[1,0]
	s_and_b32 s6, s6, 0x1c0
	s_add_i32 s2, s50, s22
	v_pk_mul_f32 v[124:125], v[126:127], v[124:125]
	v_or_b32_e32 v1, s6, v1
	v_lshlrev_b64 v[2:3], 11, v[2:3]
	s_add_i32 s13, s13, s88
	s_add_i32 s12, s12, s47
	v_pk_mul_f32 v[122:123], v[124:125], v[122:123]
	v_cvt_pk_bf16_f32 v116, v116, v117
	v_cvt_pk_bf16_f32 v117, v118, v119
	v_cvt_pk_bf16_f32 v118, v120, v121
	v_lshl_add_u64 v[2:3], s[16:17], 0, v[2:3]
	v_lshlrev_b32_e32 v120, 1, v1
	v_mov_b32_e32 v121, v0
	s_cmpk_gt_i32 s2, 0xfff
	v_cvt_pk_bf16_f32 v119, v122, v123
	v_lshl_add_u64 v[2:3], v[2:3], 0, v[120:121]
	s_cselect_b64 s[8:9], -1, 0
	s_waitcnt vmcnt(0)
	global_store_dwordx4 v[2:3], v[116:119], off
	s_nop 0

.LBB0_624:
	s_nop 0
	v_lshlrev_b32_e32 v2, 16, v40
	v_and_b32_e32 v3, 0xffff0000, v40
	v_pk_fma_f32 v[2:3], v[36:37], v[2:3], v[48:49]
	v_lshlrev_b32_e32 v116, 16, v28
	v_and_b32_e32 v117, 0xffff0000, v28
	v_pk_fma_f32 v[2:3], v[8:9], v[116:117], v[2:3]
	v_lshlrev_b32_e32 v116, 16, v52
	v_and_b32_e32 v117, 0xffff0000, v52
	v_pk_fma_f32 v[2:3], v[12:13], v[116:117], v[2:3]
	v_lshlrev_b32_e32 v116, 16, v60
	v_and_b32_e32 v117, 0xffff0000, v60
	v_pk_fma_f32 v[116:117], v[16:17], v[116:117], v[2:3]
	v_lshlrev_b32_e32 v2, 16, v42
	v_and_b32_e32 v3, 0xffff0000, v42
	v_pk_fma_f32 v[2:3], v[24:25], v[2:3], v[44:45]
	v_lshlrev_b32_e32 v118, 16, v30
	v_and_b32_e32 v119, 0xffff0000, v30
	v_pk_fma_f32 v[2:3], v[4:5], v[118:119], v[2:3]
	v_lshlrev_b32_e32 v118, 16, v54
	v_and_b32_e32 v119, 0xffff0000, v54
	v_pk_fma_f32 v[2:3], v[20:21], v[118:119], v[2:3]
	v_lshlrev_b32_e32 v118, 16, v62
	v_and_b32_e32 v119, 0xffff0000, v62
	v_pk_fma_f32 v[120:121], v[32:33], v[118:119], v[2:3]
	v_lshlrev_b32_e32 v2, 16, v41
	v_and_b32_e32 v3, 0xffff0000, v41
	v_pk_fma_f32 v[2:3], v[38:39], v[2:3], v[50:51]
	v_lshlrev_b32_e32 v118, 16, v29
	v_and_b32_e32 v119, 0xffff0000, v29
	v_pk_fma_f32 v[2:3], v[10:11], v[118:119], v[2:3]
	v_lshlrev_b32_e32 v118, 16, v53
	v_and_b32_e32 v119, 0xffff0000, v53
	v_pk_fma_f32 v[2:3], v[14:15], v[118:119], v[2:3]
	v_lshlrev_b32_e32 v118, 16, v61
	v_and_b32_e32 v119, 0xffff0000, v61
	v_pk_fma_f32 v[118:119], v[18:19], v[118:119], v[2:3]
	v_lshlrev_b32_e32 v2, 16, v43
	v_and_b32_e32 v3, 0xffff0000, v43
	v_pk_fma_f32 v[2:3], v[26:27], v[2:3], v[46:47]
	v_lshlrev_b32_e32 v122, 16, v31
	v_and_b32_e32 v123, 0xffff0000, v31
	v_pk_fma_f32 v[2:3], v[6:7], v[122:123], v[2:3]
	v_lshlrev_b32_e32 v122, 16, v55
	v_and_b32_e32 v123, 0xffff0000, v55
	v_mov_b32_e32 v152, v204
	v_pk_fma_f32 v[2:3], v[22:23], v[122:123], v[2:3]
	v_lshlrev_b32_e32 v122, 16, v63
	v_and_b32_e32 v123, 0xffff0000, v63
	v_pk_fma_f32 v[122:123], v[34:35], v[122:123], v[2:3]
	v_lshlrev_b32_e32 v1, 3, v152
	v_ashrrev_i32_e32 v2, 3, v152
	v_and_b32_e32 v1, 56, v1
	v_lshl_add_u32 v151, v2, 8, 0
	v_lshl_add_u32 v3, v1, 2, v151
	ds_write_b128 v3, v[116:119]
	ds_write_b128 v3, v[120:123] offset:16
	v_cvt_pk_bf16_f32 v116, v116, v117
	v_cvt_pk_bf16_f32 v117, v118, v119
	v_cvt_pk_bf16_f32 v118, v120, v121
	v_mul_lo_u32 v120, v2, s1
	v_lshlrev_b32_e32 v121, 1, v1
	v_and_b32_e32 v162, 15, v152
	v_cvt_pk_bf16_f32 v119, v122, v123
	v_add3_u32 v120, v151, v120, v121
	v_and_b32_e32 v153, 48, v152
	ds_write_b128 v120, v[116:119] offset:16384
	v_mul_u32_u24_e32 v116, 0x90, v162
	v_add3_u32 v163, 0, v153, v116
	s_waitcnt lgkmcnt(0)
	s_barrier
	ds_read_b128 v[128:131], v163 offset:20992
	s_waitcnt lgkmcnt(0)
	v_mfma_f32_16x16x32_bf16 v[136:139], v[56:59], v[128:131], 0
	ds_read_b128 v[116:119], v163 offset:16384
	ds_read_b128 v[124:127], v163 offset:18688
	s_add_i32 s51, 0, 0xe400
	v_mfma_f32_16x16x32_bf16 v[140:143], v[72:75], v[128:131], 0
	ds_read_b128 v[128:131], v163 offset:23296
	v_cmp_gt_u32_e32 vcc, s49, v152
	s_waitcnt lgkmcnt(0)
	v_mfma_f32_16x16x32_bf16 v[144:147], v[56:59], v[128:131], 0
	v_mfma_f32_16x16x32_bf16 v[154:157], v[72:75], v[128:131], 0
	ds_read_b128 v[128:131], v163 offset:16448
	v_mfma_f32_16x16x32_bf16 v[120:123], v[56:59], v[116:119], 0
	v_mfma_f32_16x16x32_bf16 v[116:119], v[72:75], v[116:119], 0
	s_waitcnt lgkmcnt(0)
	v_mfma_f32_16x16x32_bf16 v[158:161], v[64:67], v[128:131], v[120:123]
	v_mfma_f32_16x16x32_bf16 v[128:131], v[76:79], v[128:131], v[116:119]
	s_nop 4
	ds_read_b128 v[116:119], v163 offset:18752
	v_mfma_f32_16x16x32_bf16 v[132:135], v[56:59], v[124:127], 0
	s_nop 0
	v_add_f32_e32 v128, v84, v128
	v_mul_f32_e32 v128, 0xbfb8aa3b, v128
	v_exp_f32_e32 v128, v128
	v_mfma_f32_16x16x32_bf16 v[124:127], v[72:75], v[124:127], 0
	v_add_f32_e32 v129, v85, v129
	v_mul_f32_e32 v129, 0xbfb8aa3b, v129
	v_exp_f32_e32 v129, v129
	s_waitcnt lgkmcnt(0)
	v_mfma_f32_16x16x32_bf16 v[132:135], v[64:67], v[116:119], v[132:135]
	v_add_f32_e32 v130, v86, v130
	v_mul_f32_e32 v130, 0xbfb8aa3b, v130
	v_add_f32_e32 v128, 1.0, v128
	v_mfma_f32_16x16x32_bf16 v[124:127], v[76:79], v[116:119], v[124:127]
	ds_read_b128 v[116:119], v163 offset:21056
	s_nop 2
	v_add_f32_e32 v132, v80, v132
	v_mul_f32_e32 v132, 0xbfb8aa3b, v132
	s_waitcnt lgkmcnt(0)
	v_mfma_f32_16x16x32_bf16 v[136:139], v[64:67], v[116:119], v[136:139]
	v_exp_f32_e32 v132, v132
	v_add_f32_e32 v133, v81, v133
	v_mul_f32_e32 v133, 0xbfb8aa3b, v133
	v_mfma_f32_16x16x32_bf16 v[120:123], v[76:79], v[116:119], v[140:143]
	ds_read_b128 v[116:119], v163 offset:23360
	v_exp_f32_e32 v133, v133
	v_add_f32_e32 v134, v82, v134
	s_waitcnt lgkmcnt(0)
	v_mfma_f32_16x16x32_bf16 v[140:143], v[64:67], v[116:119], v[144:147]
	v_mul_f32_e32 v134, 0xbfb8aa3b, v134
	s_nop 1
	v_mov_b32_e32 v144, s51
	v_mov_b32_e32 v145, s81
	v_cndmask_b32_e32 v144, v144, v145, vcc
	v_lshlrev_b32_e32 v145, 7, v152
	v_and_b32_e32 v145, 0x4000, v145
	v_lshlrev_b32_e32 v146, 8, v162
	v_add3_u32 v144, v144, v145, v146
	v_add_f32_e32 v146, v80, v158
	v_mul_f32_e32 v146, 0xbfb8aa3b, v146
	v_add_f32_e32 v147, v81, v159
	v_exp_f32_e32 v146, v146
	v_mul_f32_e32 v147, 0xbfb8aa3b, v147
	v_exp_f32_e32 v147, v147
	v_lshlrev_b32_e32 v145, 1, v152
	v_and_b32_e32 v145, 0x80, v145
	v_add_f32_e32 v146, 1.0, v146
	v_rcp_f32_e32 v146, v146
	v_add3_u32 v153, v144, v145, v153
	v_xor_b32_e32 v153, v201, v153
	v_add_f32_e32 v144, 1.0, v147
	v_add_f32_e32 v147, v82, v160
	v_mul_f32_e32 v147, 0xbfb8aa3b, v147
	v_mfma_f32_16x16x32_bf16 v[116:119], v[76:79], v[116:119], v[154:157]
	v_rcp_f32_e32 v145, v144
	v_exp_f32_e32 v147, v147

	s_nop 0
	v_add_f32_e32 v154, v83, v161
	v_mul_f32_e32 v154, 0xbfb8aa3b, v154
	v_exp_f32_e32 v154, v154
	s_nop 0

	v_mul_f32_e32 v144, v240, v146

	v_add_f32_e32 v147, 1.0, v147

	v_rcp_f32_e32 v147, v147
	v_mul_f32_e32 v145, v241, v145
	v_add_f32_e32 v146, 1.0, v154
	v_rcp_f32_e32 v154, v146

	v_add_f32_e32 v132, 1.0, v132
	v_exp_f32_e32 v134, v134
	v_add_f32_e32 v135, v83, v135

	v_rcp_f32_e32 v132, v132
	v_mul_f32_e32 v135, 0xbfb8aa3b, v135
	v_mul_f32_e32 v146, v242, v147

	v_add_f32_e32 v133, 1.0, v133
	v_exp_f32_e32 v135, v135

	v_rcp_f32_e32 v133, v133
	v_mul_f32_e32 v147, v243, v154
	v_add_f32_e32 v134, 1.0, v134
	v_add_f32_e32 v136, v80, v136
	ds_write_b128 v153, v[144:147]

	v_rcp_f32_e32 v134, v134
	v_mul_f32_e32 v136, 0xbfb8aa3b, v136

	v_add_f32_e32 v135, 1.0, v135
	v_exp_f32_e32 v136, v136
	v_mul_f32_e32 v132, v240, v132

	v_rcp_f32_e32 v135, v135

	v_add_f32_e32 v137, v81, v137
	v_mul_f32_e32 v133, v241, v133

	v_mul_f32_e32 v137, 0xbfb8aa3b, v137

	v_exp_f32_e32 v137, v137
	v_add_f32_e32 v136, 1.0, v136
	v_mul_f32_e32 v134, v242, v134

	v_rcp_f32_e32 v136, v136

	v_mul_f32_e32 v135, v243, v135
	ds_write_b128 v153, v[132:135] offset:4096
	v_add_f32_e32 v132, 1.0, v137
	v_rcp_f32_e32 v133, v132

	v_add_f32_e32 v135, v82, v138

	v_mul_f32_e32 v135, 0xbfb8aa3b, v135
	v_mul_f32_e32 v132, v240, v136
	v_exp_f32_e32 v135, v135
	v_add_f32_e32 v136, v83, v139
	v_mul_f32_e32 v136, 0xbfb8aa3b, v136
	v_exp_f32_e32 v136, v136

	v_add_f32_e32 v135, 1.0, v135

	v_rcp_f32_e32 v135, v135
	v_mul_f32_e32 v133, v241, v133
	v_add_f32_e32 v134, 1.0, v136
	v_rcp_f32_e32 v136, v134


	v_mul_f32_e32 v134, v242, v135


	v_mul_f32_e32 v135, v243, v136
	v_add_f32_e32 v136, v80, v140
	v_mul_f32_e32 v136, 0xbfb8aa3b, v136
	v_exp_f32_e32 v136, v136
	v_add_f32_e32 v137, v81, v141
	v_mul_f32_e32 v137, 0xbfb8aa3b, v137
	v_exp_f32_e32 v137, v137
	v_add_f32_e32 v136, 1.0, v136
	v_rcp_f32_e32 v136, v136
	ds_write_b128 v153, v[132:135] offset:8192
	v_add_f32_e32 v132, 1.0, v137
	v_rcp_f32_e32 v133, v132

	v_add_f32_e32 v135, v82, v142

	v_mul_f32_e32 v135, 0xbfb8aa3b, v135
	v_mul_f32_e32 v132, v240, v136
	v_exp_f32_e32 v135, v135
	v_add_f32_e32 v136, v83, v143
	v_mul_f32_e32 v136, 0xbfb8aa3b, v136
	v_exp_f32_e32 v136, v136

	v_add_f32_e32 v135, 1.0, v135

	v_rcp_f32_e32 v135, v135
	v_mul_f32_e32 v133, v241, v133
	v_add_f32_e32 v134, 1.0, v136
	v_rcp_f32_e32 v136, v134

	v_exp_f32_e32 v130, v130
	v_add_f32_e32 v131, v87, v131

	v_rcp_f32_e32 v128, v128
	v_mul_f32_e32 v131, 0xbfb8aa3b, v131
	v_mul_f32_e32 v134, v242, v135

	v_add_f32_e32 v129, 1.0, v129
	v_exp_f32_e32 v131, v131

	v_rcp_f32_e32 v129, v129
	v_add_f32_e32 v124, v84, v124
	v_mul_f32_e32 v135, v243, v136
	v_add_f32_e32 v130, 1.0, v130
	v_mul_f32_e32 v124, 0xbfb8aa3b, v124
	ds_write_b128 v153, v[132:135] offset:12288

	v_rcp_f32_e32 v130, v130
	v_exp_f32_e32 v124, v124
	v_add_f32_e32 v125, v85, v125
	s_nop 0

	v_add_f32_e32 v131, 1.0, v131
	v_mul_f32_e32 v125, 0xbfb8aa3b, v125
	v_mul_f32_e32 v128, v244, v128

	v_rcp_f32_e32 v131, v131
	v_exp_f32_e32 v125, v125
	v_add_f32_e32 v126, v86, v126

	v_mul_f32_e32 v126, 0xbfb8aa3b, v126
	v_mul_f32_e32 v129, v245, v129

	v_add_f32_e32 v124, 1.0, v124
	v_exp_f32_e32 v126, v126
	v_add_f32_e32 v127, v87, v127

	v_rcp_f32_e32 v124, v124
	v_mul_f32_e32 v127, 0xbfb8aa3b, v127
	v_mul_f32_e32 v130, v246, v130

	v_add_f32_e32 v125, 1.0, v125
	v_exp_f32_e32 v127, v127

	v_rcp_f32_e32 v125, v125
	v_add_f32_e32 v120, v84, v120
	v_mul_f32_e32 v131, v247, v131
	v_add_f32_e32 v126, 1.0, v126
	v_mul_f32_e32 v120, 0xbfb8aa3b, v120
	ds_write_b128 v153, v[128:131] offset:64

	v_rcp_f32_e32 v126, v126
	v_exp_f32_e32 v120, v120
	v_add_f32_e32 v121, v85, v121

	v_add_f32_e32 v127, 1.0, v127
	v_mul_f32_e32 v121, 0xbfb8aa3b, v121
	v_mul_f32_e32 v124, v244, v124

	v_rcp_f32_e32 v127, v127
	v_exp_f32_e32 v121, v121
	v_add_f32_e32 v122, v86, v122

	v_mul_f32_e32 v122, 0xbfb8aa3b, v122
	v_mul_f32_e32 v125, v245, v125

	v_add_f32_e32 v120, 1.0, v120
	v_exp_f32_e32 v122, v122
	v_add_f32_e32 v123, v87, v123

	v_rcp_f32_e32 v120, v120
	v_mul_f32_e32 v123, 0xbfb8aa3b, v123
	v_mul_f32_e32 v126, v246, v126

	v_add_f32_e32 v121, 1.0, v121
	v_exp_f32_e32 v123, v123

	v_rcp_f32_e32 v121, v121
	v_add_f32_e32 v116, v84, v116
	v_mul_f32_e32 v127, v247, v127
	v_add_f32_e32 v122, 1.0, v122
	v_mul_f32_e32 v116, 0xbfb8aa3b, v116
	ds_write_b128 v153, v[124:127] offset:4160

	v_rcp_f32_e32 v122, v122
	v_exp_f32_e32 v116, v116
	v_add_f32_e32 v117, v85, v117

	v_add_f32_e32 v123, 1.0, v123
	v_mul_f32_e32 v117, 0xbfb8aa3b, v117
	v_mul_f32_e32 v120, v244, v120

	v_rcp_f32_e32 v123, v123
	v_exp_f32_e32 v117, v117
	v_add_f32_e32 v118, v86, v118

	v_mul_f32_e32 v118, 0xbfb8aa3b, v118
	v_mul_f32_e32 v121, v245, v121

	v_add_f32_e32 v116, 1.0, v116
	v_exp_f32_e32 v118, v118
	v_add_f32_e32 v119, v87, v119

	v_rcp_f32_e32 v116, v116
	v_mul_f32_e32 v119, 0xbfb8aa3b, v119
	v_mul_f32_e32 v122, v246, v122

	v_add_f32_e32 v117, 1.0, v117
	v_exp_f32_e32 v119, v119

	v_rcp_f32_e32 v117, v117
	v_mul_f32_e32 v123, v247, v123
	v_add_f32_e32 v118, 1.0, v118
	ds_write_b128 v153, v[120:123] offset:8256

	v_rcp_f32_e32 v118, v118

	v_add_f32_e32 v119, 1.0, v119
	v_mul_f32_e32 v116, v244, v116

	v_rcp_f32_e32 v119, v119

	v_mul_f32_e32 v117, v245, v117


	v_mul_f32_e32 v118, v246, v118


	v_mul_f32_e32 v119, v247, v119
	v_lshlrev_b32_e32 v133, 2, v152
	ds_write_b128 v153, v[116:119] offset:12352
	v_and_b32_e32 v116, 60, v133
	v_lshlrev_b32_e32 v132, 2, v116
	v_lshlrev_b32_e32 v116, 4, v152
	v_and_b32_e32 v117, 0xffffc000, v116
	v_add_u32_e32 v117, 0, v117
	v_and_b32_e32 v116, 0x3f00, v116
	v_add3_u32 v135, v117, v116, v132
	v_xor_b32_e32 v135, v200, v135
	s_waitcnt lgkmcnt(0)
	s_barrier
	ds_read_b128 v[128:131], v135 offset:25600
	ds_read_b128 v[120:123], v135 offset:58368
	v_add_u32_e32 v134, 0, v132
	v_add_u32_e32 v136, v134, v116
	ds_read_b128 v[124:127], v136
	s_waitcnt lgkmcnt(2)
	v_mul_f32_e32 v116, 0x3fb8aa3b, v128
	v_exp_f32_e32 v116, v116
	v_add_f32_e32 v117, v128, v128
	v_cmp_nlt_f32_e32 vcc, s79, v117
	s_and_saveexec_b64 s[8:9], vcc
	s_xor_b64 s[8:9], exec, s[8:9]
	v_fma_f32 v128, -v116, v116, 1.0
	s_andn2_saveexec_b64 s[8:9], s[8:9]
	v_fmamk_f32 v118, v117, 0x3c088889, v148
	v_fmaak_f32 v118, v117, v118, 0x3e2aaaab
	v_fma_f32 v118, v117, v118, 0.5
	v_fma_f32 v118, v117, v118, 1.0
	v_mul_f32_e64 v128, v118, -v117
	s_or_b64 exec, exec, s[8:9]
	v_mul_f32_e32 v117, 0x3fb8aa3b, v129
	v_exp_f32_e32 v117, v117
	v_add_f32_e32 v118, v129, v129
	v_cmp_nlt_f32_e32 vcc, s79, v118
	s_and_saveexec_b64 s[8:9], vcc
	s_xor_b64 s[8:9], exec, s[8:9]
	v_fma_f32 v129, -v117, v117, 1.0
	s_andn2_saveexec_b64 s[8:9], s[8:9]
	v_fmamk_f32 v119, v118, 0x3c088889, v148
	v_fmaak_f32 v119, v118, v119, 0x3e2aaaab
	v_fma_f32 v119, v118, v119, 0.5
	v_fma_f32 v119, v118, v119, 1.0
	v_mul_f32_e64 v129, v119, -v118
	s_or_b64 exec, exec, s[8:9]
	v_mul_f32_e32 v118, 0x3fb8aa3b, v130
	v_exp_f32_e32 v118, v118
	v_add_f32_e32 v119, v130, v130
	v_cmp_nlt_f32_e32 vcc, s79, v119
	s_and_saveexec_b64 s[8:9], vcc
	s_xor_b64 s[8:9], exec, s[8:9]
	v_fma_f32 v130, -v118, v118, 1.0
	s_andn2_saveexec_b64 s[8:9], s[8:9]
	v_fmamk_f32 v130, v119, 0x3c088889, v148
	v_fmaak_f32 v130, v119, v130, 0x3e2aaaab
	v_fma_f32 v130, v119, v130, 0.5
	v_fma_f32 v130, v119, v130, 1.0
	v_mul_f32_e64 v130, v130, -v119
	s_or_b64 exec, exec, s[8:9]
	v_mul_f32_e32 v119, 0x3fb8aa3b, v131
	v_exp_f32_e32 v119, v119
	v_add_f32_e32 v137, v131, v131
	v_cmp_nlt_f32_e32 vcc, s79, v137
	s_and_saveexec_b64 s[8:9], vcc
	s_xor_b64 s[8:9], exec, s[8:9]
	v_fma_f32 v131, -v119, v119, 1.0
	s_andn2_saveexec_b64 s[8:9], s[8:9]
	v_fmamk_f32 v131, v137, 0x3c088889, v148
	v_fmaak_f32 v131, v137, v131, 0x3e2aaaab
	v_fma_f32 v131, v137, v131, 0.5
	v_fma_f32 v131, v137, v131, 1.0
	v_mul_f32_e64 v131, v131, -v137
	s_or_b64 exec, exec, s[8:9]
	v_max_f32_e32 v128, v128, v128
	v_max_f32_e32 v128, 0, v128
	v_sqrt_f32_e32 v128, v128
	v_max_f32_e32 v129, v129, v129
	v_max_f32_e32 v129, 0, v129
	v_sqrt_f32_e32 v129, v129
	s_waitcnt lgkmcnt(1)
	v_mul_f32_e32 v120, v120, v128
	s_waitcnt lgkmcnt(0)
	v_mul_f32_e32 v120, v124, v120
	v_max_f32_e32 v124, v130, v130
	v_max_f32_e32 v128, v131, v131
	v_max_f32_e32 v124, 0, v124
	v_max_f32_e32 v128, 0, v128
	v_sqrt_f32_e32 v124, v124
	v_sqrt_f32_e32 v128, v128
	v_mul_f32_e32 v121, v121, v129
	v_mul_f32_e32 v121, v125, v121
	v_mul_f32_e32 v122, v122, v124
	v_mul_f32_e32 v123, v123, v128
	v_mul_f32_e32 v122, v126, v122
	v_mul_f32_e32 v123, v127, v123
	ds_write_b128 v135, v[116:119] offset:25600
	ds_write_b128 v135, v[120:123] offset:58368
	v_add_u32_e32 v116, 0x800, v133
	v_and_b32_e32 v117, 0x3ffff000, v116
	v_and_b32_e32 v116, 0xfc0, v116
	v_lshl_add_u32 v117, v117, 2, 0
	v_lshlrev_b32_e32 v116, 2, v116
	v_add3_u32 v137, v117, v116, v132
	v_xor_b32_e32 v137, v200, v137
	ds_read_b128 v[128:131], v137 offset:25600
	ds_read_b128 v[120:123], v137 offset:58368
	v_add_u32_e32 v116, v134, v116
	ds_read_b128 v[124:127], v116
	s_waitcnt lgkmcnt(2)
	v_mul_f32_e32 v116, 0x3fb8aa3b, v128
	v_exp_f32_e32 v116, v116
	v_add_f32_e32 v117, v128, v128
	v_cmp_nlt_f32_e32 vcc, s79, v117
	s_and_saveexec_b64 s[8:9], vcc
	s_xor_b64 s[8:9], exec, s[8:9]
	v_fma_f32 v128, -v116, v116, 1.0
	s_andn2_saveexec_b64 s[8:9], s[8:9]
	v_fmamk_f32 v118, v117, 0x3c088889, v148
	v_fmaak_f32 v118, v117, v118, 0x3e2aaaab
	v_fma_f32 v118, v117, v118, 0.5
	v_fma_f32 v118, v117, v118, 1.0
	v_mul_f32_e64 v128, v118, -v117
	s_or_b64 exec, exec, s[8:9]
	v_mul_f32_e32 v117, 0x3fb8aa3b, v129
	v_exp_f32_e32 v117, v117
	v_add_f32_e32 v118, v129, v129
	v_cmp_nlt_f32_e32 vcc, s79, v118
	s_and_saveexec_b64 s[8:9], vcc
	s_xor_b64 s[8:9], exec, s[8:9]
	v_fma_f32 v129, -v117, v117, 1.0
	s_andn2_saveexec_b64 s[8:9], s[8:9]
	v_fmamk_f32 v119, v118, 0x3c088889, v148
	v_fmaak_f32 v119, v118, v119, 0x3e2aaaab
	v_fma_f32 v119, v118, v119, 0.5
	v_fma_f32 v119, v118, v119, 1.0
	v_mul_f32_e64 v129, v119, -v118
	s_or_b64 exec, exec, s[8:9]
	v_mul_f32_e32 v118, 0x3fb8aa3b, v130
	v_exp_f32_e32 v118, v118
	v_add_f32_e32 v119, v130, v130
	v_cmp_nlt_f32_e32 vcc, s79, v119
	s_and_saveexec_b64 s[8:9], vcc
	s_xor_b64 s[8:9], exec, s[8:9]
	v_fma_f32 v130, -v118, v118, 1.0
	s_andn2_saveexec_b64 s[8:9], s[8:9]
	v_fmamk_f32 v130, v119, 0x3c088889, v148
	v_fmaak_f32 v130, v119, v130, 0x3e2aaaab
	v_fma_f32 v130, v119, v130, 0.5
	v_fma_f32 v130, v119, v130, 1.0
	v_mul_f32_e64 v130, v130, -v119
	s_or_b64 exec, exec, s[8:9]
	v_mul_f32_e32 v119, 0x3fb8aa3b, v131
	v_exp_f32_e32 v119, v119
	v_add_f32_e32 v138, v131, v131
	v_cmp_nlt_f32_e32 vcc, s79, v138
	s_and_saveexec_b64 s[8:9], vcc
	s_xor_b64 s[8:9], exec, s[8:9]
	v_fma_f32 v131, -v119, v119, 1.0
	s_andn2_saveexec_b64 s[8:9], s[8:9]
	v_fmamk_f32 v131, v138, 0x3c088889, v148
	v_fmaak_f32 v131, v138, v131, 0x3e2aaaab
	v_fma_f32 v131, v138, v131, 0.5
	v_fma_f32 v131, v138, v131, 1.0
	v_mul_f32_e64 v131, v131, -v138
	s_or_b64 exec, exec, s[8:9]
	v_max_f32_e32 v128, v128, v128
	v_max_f32_e32 v128, 0, v128
	v_sqrt_f32_e32 v128, v128
	v_max_f32_e32 v129, v129, v129
	v_max_f32_e32 v129, 0, v129
	v_sqrt_f32_e32 v129, v129
	s_waitcnt lgkmcnt(1)
	v_mul_f32_e32 v120, v120, v128
	s_waitcnt lgkmcnt(0)
	v_mul_f32_e32 v120, v124, v120
	v_max_f32_e32 v124, v130, v130
	v_max_f32_e32 v128, v131, v131
	v_max_f32_e32 v124, 0, v124
	v_max_f32_e32 v128, 0, v128
	v_sqrt_f32_e32 v124, v124
	v_sqrt_f32_e32 v128, v128
	v_mul_f32_e32 v121, v121, v129
	v_mul_f32_e32 v121, v125, v121
	v_mul_f32_e32 v122, v122, v124
	v_mul_f32_e32 v123, v123, v128
	v_mul_f32_e32 v122, v126, v122
	v_mul_f32_e32 v123, v127, v123
	ds_write_b128 v137, v[116:119] offset:25600
	ds_write_b128 v137, v[120:123] offset:58368
	ds_read_b128 v[128:131], v135 offset:41984
	v_add_u32_e32 v137, 0xe400, v135
	ds_read_b128 v[120:123], v137 offset:16384
	ds_read_b128 v[124:127], v136
	s_waitcnt lgkmcnt(2)
	v_mul_f32_e32 v116, 0x3fb8aa3b, v128
	v_exp_f32_e32 v116, v116
	v_add_f32_e32 v117, v128, v128
	v_cmp_nlt_f32_e32 vcc, s79, v117
	s_and_saveexec_b64 s[8:9], vcc
	s_xor_b64 s[8:9], exec, s[8:9]
	v_fma_f32 v128, -v116, v116, 1.0
	s_andn2_saveexec_b64 s[8:9], s[8:9]
	v_fmamk_f32 v118, v117, 0x3c088889, v148
	v_fmaak_f32 v118, v117, v118, 0x3e2aaaab
	v_fma_f32 v118, v117, v118, 0.5
	v_fma_f32 v118, v117, v118, 1.0
	v_mul_f32_e64 v128, v118, -v117
	s_or_b64 exec, exec, s[8:9]
	v_mul_f32_e32 v117, 0x3fb8aa3b, v129
	v_exp_f32_e32 v117, v117
	v_add_f32_e32 v118, v129, v129
	v_cmp_nlt_f32_e32 vcc, s79, v118
	s_and_saveexec_b64 s[8:9], vcc
	s_xor_b64 s[8:9], exec, s[8:9]
	v_fma_f32 v129, -v117, v117, 1.0
	s_andn2_saveexec_b64 s[8:9], s[8:9]
	v_fmamk_f32 v119, v118, 0x3c088889, v148
	v_fmaak_f32 v119, v118, v119, 0x3e2aaaab
	v_fma_f32 v119, v118, v119, 0.5
	v_fma_f32 v119, v118, v119, 1.0
	v_mul_f32_e64 v129, v119, -v118
	s_or_b64 exec, exec, s[8:9]
	v_mul_f32_e32 v118, 0x3fb8aa3b, v130
	v_exp_f32_e32 v118, v118
	v_add_f32_e32 v119, v130, v130
	v_cmp_nlt_f32_e32 vcc, s79, v119
	s_and_saveexec_b64 s[8:9], vcc
	s_xor_b64 s[8:9], exec, s[8:9]
	v_fma_f32 v130, -v118, v118, 1.0
	s_andn2_saveexec_b64 s[8:9], s[8:9]
	v_fmamk_f32 v130, v119, 0x3c088889, v148
	v_fmaak_f32 v130, v119, v130, 0x3e2aaaab
	v_fma_f32 v130, v119, v130, 0.5
	v_fma_f32 v130, v119, v130, 1.0
	v_mul_f32_e64 v130, v130, -v119
	s_or_b64 exec, exec, s[8:9]
	v_mul_f32_e32 v119, 0x3fb8aa3b, v131
	v_exp_f32_e32 v119, v119
	v_add_f32_e32 v136, v131, v131
	v_cmp_nlt_f32_e32 vcc, s79, v136
	s_and_saveexec_b64 s[8:9], vcc
	s_xor_b64 s[8:9], exec, s[8:9]
	v_fma_f32 v131, -v119, v119, 1.0
	s_andn2_saveexec_b64 s[8:9], s[8:9]
	v_fmamk_f32 v131, v136, 0x3c088889, v148
	v_fmaak_f32 v131, v136, v131, 0x3e2aaaab
	v_fma_f32 v131, v136, v131, 0.5
	v_fma_f32 v131, v136, v131, 1.0
	v_mul_f32_e64 v131, v131, -v136
	s_or_b64 exec, exec, s[8:9]
	v_max_f32_e32 v128, v128, v128
	v_max_f32_e32 v128, 0, v128
	v_sqrt_f32_e32 v128, v128
	v_max_f32_e32 v129, v129, v129
	v_max_f32_e32 v129, 0, v129
	v_sqrt_f32_e32 v129, v129
	s_waitcnt lgkmcnt(1)
	v_mul_f32_e32 v120, v120, v128
	s_waitcnt lgkmcnt(0)
	v_mul_f32_e32 v120, v124, v120
	v_max_f32_e32 v124, v130, v130
	v_max_f32_e32 v128, v131, v131
	v_max_f32_e32 v124, 0, v124
	v_max_f32_e32 v128, 0, v128
	v_sqrt_f32_e32 v124, v124
	v_sqrt_f32_e32 v128, v128
	v_mul_f32_e32 v121, v121, v129
	v_mul_f32_e32 v121, v125, v121
	v_mul_f32_e32 v122, v122, v124
	v_mul_f32_e32 v123, v123, v128
	v_mul_f32_e32 v122, v126, v122
	v_mul_f32_e32 v123, v127, v123
	ds_write_b128 v135, v[116:119] offset:41984
	ds_write_b128 v137, v[120:123] offset:16384
	v_add_u32_e32 v116, 0x1800, v133
	v_and_b32_e32 v117, 0x3ffff000, v116
	v_and_b32_e32 v116, 0xfc0, v116
	v_lshl_add_u32 v117, v117, 2, 0
	v_lshlrev_b32_e32 v116, 2, v116
	v_add3_u32 v132, v117, v116, v132
	v_xor_b32_e32 v132, v200, v132
	ds_read_b128 v[128:131], v132 offset:25600
	ds_read_b128 v[120:123], v132 offset:58368
	v_add_u32_e32 v116, v134, v116
	ds_read_b128 v[124:127], v116
	s_waitcnt lgkmcnt(2)
	v_mul_f32_e32 v116, 0x3fb8aa3b, v128
	v_exp_f32_e32 v116, v116
	v_add_f32_e32 v117, v128, v128
	v_cmp_nlt_f32_e32 vcc, s79, v117
	s_and_saveexec_b64 s[8:9], vcc
	s_xor_b64 s[8:9], exec, s[8:9]
	v_fma_f32 v128, -v116, v116, 1.0
	s_andn2_saveexec_b64 s[8:9], s[8:9]
	v_fmamk_f32 v118, v117, 0x3c088889, v148
	v_fmaak_f32 v118, v117, v118, 0x3e2aaaab
	v_fma_f32 v118, v117, v118, 0.5
	v_fma_f32 v118, v117, v118, 1.0
	v_mul_f32_e64 v128, v118, -v117
	s_or_b64 exec, exec, s[8:9]
	v_mul_f32_e32 v117, 0x3fb8aa3b, v129
	v_exp_f32_e32 v117, v117
	v_add_f32_e32 v118, v129, v129
	v_cmp_nlt_f32_e32 vcc, s79, v118
	s_and_saveexec_b64 s[8:9], vcc
	s_xor_b64 s[8:9], exec, s[8:9]
	v_fma_f32 v129, -v117, v117, 1.0
	s_andn2_saveexec_b64 s[8:9], s[8:9]
	v_fmamk_f32 v119, v118, 0x3c088889, v148
	v_fmaak_f32 v119, v118, v119, 0x3e2aaaab
	v_fma_f32 v119, v118, v119, 0.5
	v_fma_f32 v119, v118, v119, 1.0
	v_mul_f32_e64 v129, v119, -v118
	s_or_b64 exec, exec, s[8:9]
	v_mul_f32_e32 v118, 0x3fb8aa3b, v130
	v_exp_f32_e32 v118, v118
	v_add_f32_e32 v119, v130, v130
	v_cmp_nlt_f32_e32 vcc, s79, v119
	s_and_saveexec_b64 s[8:9], vcc
	s_xor_b64 s[8:9], exec, s[8:9]
	v_fma_f32 v130, -v118, v118, 1.0
	s_andn2_saveexec_b64 s[8:9], s[8:9]
	v_fmamk_f32 v130, v119, 0x3c088889, v148
	v_fmaak_f32 v130, v119, v130, 0x3e2aaaab
	v_fma_f32 v130, v119, v130, 0.5
	v_fma_f32 v130, v119, v130, 1.0
	v_mul_f32_e64 v130, v130, -v119
	s_or_b64 exec, exec, s[8:9]
	v_mul_f32_e32 v119, 0x3fb8aa3b, v131
	v_exp_f32_e32 v119, v119
	v_add_f32_e32 v133, v131, v131
	v_cmp_nlt_f32_e32 vcc, s79, v133
	s_and_saveexec_b64 s[8:9], vcc
	s_xor_b64 s[8:9], exec, s[8:9]
	v_fma_f32 v131, -v119, v119, 1.0
	s_andn2_saveexec_b64 s[8:9], s[8:9]
	v_fmamk_f32 v131, v133, 0x3c088889, v148
	v_fmaak_f32 v131, v133, v131, 0x3e2aaaab
	v_fma_f32 v131, v133, v131, 0.5
	v_fma_f32 v131, v133, v131, 1.0
	v_mul_f32_e64 v131, v131, -v133
	s_or_b64 exec, exec, s[8:9]
	v_max_f32_e32 v128, v128, v128
	v_max_f32_e32 v128, 0, v128
	v_sqrt_f32_e32 v128, v128
	v_max_f32_e32 v129, v129, v129
	v_max_f32_e32 v129, 0, v129
	v_sqrt_f32_e32 v129, v129
	s_waitcnt lgkmcnt(1)
	v_mul_f32_e32 v120, v120, v128
	v_max_f32_e32 v128, v130, v130
	s_waitcnt lgkmcnt(0)
	v_mul_f32_e32 v120, v124, v120
	v_max_f32_e32 v124, v131, v131
	v_max_f32_e32 v128, 0, v128
	v_max_f32_e32 v124, 0, v124
	v_sqrt_f32_e32 v128, v128
	v_sqrt_f32_e32 v124, v124
	v_ashrrev_i32_e32 v156, 7, v152
	v_mul_f32_e32 v121, v121, v129
	v_mul_f32_e32 v122, v122, v128
	v_and_b32_e32 v172, 0x7f, v152
	v_mul_f32_e32 v123, v123, v124
	v_lshlrev_b32_e32 v146, 4, v156
	v_mul_f32_e32 v121, v125, v121
	v_mul_f32_e32 v122, v126, v122
	v_bfe_u32 v153, v152, 6, 1
	v_mul_f32_e32 v123, v127, v123
	ds_write_b128 v132, v[116:119] offset:25600
	ds_write_b128 v132, v[120:123] offset:58368
	v_and_b32_e32 v154, 63, v152
	v_sub_u32_e32 v116, 63, v146
	v_cmp_gt_u32_e32 vcc, 64, v172
	v_or_b32_e32 v118, 1, v146

	s_nop 0
	v_cndmask_b32_e32 v155, v116, v146, vcc
	v_sub_u32_e32 v119, 63, v118
	v_or_b32_e32 v120, 2, v146

	v_cndmask_b32_e32 v157, v119, v118, vcc
	v_sub_u32_e32 v121, 63, v120
	v_or_b32_e32 v122, 3, v146


	v_cndmask_b32_e32 v158, v121, v120, vcc
	v_sub_u32_e32 v123, 63, v122
	v_or_b32_e32 v124, 4, v146
	s_waitcnt lgkmcnt(0)
	s_barrier
	ds_read2st64_b32 v[116:117], v176 offset0:100 offset1:228


	v_cndmask_b32_e32 v159, v123, v122, vcc
	v_sub_u32_e32 v125, 63, v124
	v_or_b32_e32 v126, 5, v146
	ds_read2st64_b32 v[118:119], v177 offset0:100 offset1:228


	v_cndmask_b32_e32 v160, v125, v124, vcc
	v_sub_u32_e32 v127, 63, v126
	v_or_b32_e32 v128, 6, v146
	ds_read2st64_b32 v[120:121], v178 offset0:100 offset1:228


	v_cndmask_b32_e32 v161, v127, v126, vcc
	v_sub_u32_e32 v129, 63, v128
	v_or_b32_e32 v130, 7, v146
	ds_read2st64_b32 v[122:123], v179 offset0:100 offset1:228


	v_cndmask_b32_e32 v162, v129, v128, vcc
	v_sub_u32_e32 v131, 63, v130
	v_or_b32_e32 v132, 8, v146
	ds_read2st64_b32 v[124:125], v180 offset0:100 offset1:228


	v_cndmask_b32_e32 v163, v131, v130, vcc
	v_sub_u32_e32 v133, 63, v132
	v_or_b32_e32 v134, 9, v146
	ds_read2st64_b32 v[126:127], v181 offset0:100 offset1:228


	v_cndmask_b32_e32 v164, v133, v132, vcc
	v_sub_u32_e32 v135, 63, v134
	v_or_b32_e32 v136, 10, v146
	s_waitcnt lgkmcnt(5)
	v_fma_f32 v173, 0, v116, v117
	ds_read2st64_b32 v[128:129], v182 offset0:100 offset1:228


	v_cndmask_b32_e32 v165, v135, v134, vcc
	v_sub_u32_e32 v137, 63, v136
	v_or_b32_e32 v138, 11, v146
	s_waitcnt lgkmcnt(5)
	v_fma_f32 v173, v173, v118, v119
	ds_read2st64_b32 v[130:131], v183 offset0:100 offset1:228


	v_cndmask_b32_e32 v166, v137, v136, vcc
	v_sub_u32_e32 v139, 63, v138
	v_or_b32_e32 v140, 12, v146
	v_mul_f32_e32 v174, v116, v118
	s_waitcnt lgkmcnt(5)
	v_fma_f32 v173, v173, v120, v121
	ds_read2st64_b32 v[132:133], v184 offset0:100 offset1:228


	v_cndmask_b32_e32 v167, v139, v138, vcc
	v_sub_u32_e32 v141, 63, v140
	v_or_b32_e32 v142, 13, v146
	v_mul_f32_e32 v174, v174, v120
	s_waitcnt lgkmcnt(5)
	v_fma_f32 v173, v173, v122, v123
	ds_read2st64_b32 v[134:135], v185 offset0:100 offset1:228


	v_cndmask_b32_e32 v168, v141, v140, vcc
	v_sub_u32_e32 v143, 63, v142
	v_or_b32_e32 v144, 14, v146
	v_mul_f32_e32 v174, v174, v122
	s_waitcnt lgkmcnt(5)
	v_fma_f32 v173, v173, v124, v125
	ds_read2st64_b32 v[136:137], v186 offset0:100 offset1:228


	v_cndmask_b32_e32 v169, v143, v142, vcc
	v_sub_u32_e32 v145, 63, v144
	v_or_b32_e32 v146, 15, v146
	v_mul_f32_e32 v174, v174, v124
	s_waitcnt lgkmcnt(5)
	v_fma_f32 v173, v173, v126, v127
	ds_read2st64_b32 v[138:139], v187 offset0:100 offset1:228


	v_cndmask_b32_e32 v170, v145, v144, vcc
	v_sub_u32_e32 v171, 63, v146
	v_mul_f32_e32 v174, v174, v126
	s_waitcnt lgkmcnt(5)
	v_fma_f32 v173, v173, v128, v129
	ds_read2st64_b32 v[140:141], v188 offset0:100 offset1:228


	v_cndmask_b32_e32 v171, v171, v146, vcc
	v_mul_f32_e32 v174, v174, v128
	s_waitcnt lgkmcnt(5)
	v_fma_f32 v173, v173, v130, v131
	ds_read2st64_b32 v[142:143], v189 offset0:100 offset1:228


	v_mul_f32_e32 v174, v174, v130
	s_waitcnt lgkmcnt(5)
	v_fma_f32 v173, v173, v132, v133
	ds_read2st64_b32 v[144:145], v190 offset0:100 offset1:228

	v_mul_f32_e32 v174, v174, v132
	s_waitcnt lgkmcnt(5)
	v_fma_f32 v173, v173, v134, v135
	ds_read2st64_b32 v[146:147], v191 offset0:100 offset1:228
	v_mul_f32_e32 v174, v174, v134
	s_waitcnt lgkmcnt(5)
	v_fma_f32 v173, v173, v136, v137
	v_mul_f32_e32 v174, v174, v136
	s_waitcnt lgkmcnt(4)
	v_fma_f32 v173, v173, v138, v139
	v_mul_f32_e32 v174, v174, v138
	s_waitcnt lgkmcnt(3)
	v_fma_f32 v173, v173, v140, v141
	v_mul_f32_e32 v174, v174, v140
	s_waitcnt lgkmcnt(2)
	v_fma_f32 v173, v173, v142, v143
	v_mul_f32_e32 v174, v174, v142
	s_waitcnt lgkmcnt(1)
	v_fma_f32 v173, v173, v144, v145
	v_lshl_add_u32 v152, v152, 2, 0
	v_mul_f32_e32 v174, v174, v144
	s_waitcnt lgkmcnt(0)
	v_fma_f32 v173, v173, v146, v147
	v_add_u32_e32 v175, 0x16400, v152
	v_add_u32_e32 v152, 0x16c00, v152
	v_mul_f32_e32 v174, v174, v146
	ds_write_b32 v152, v173
	v_cmp_lt_i32_e32 vcc, 0, v156
	v_lshl_add_u32 v172, v172, 2, 0
	v_mov_b32_e32 v152, v149
	ds_write_b32 v175, v174
	s_waitcnt lgkmcnt(0)
	s_barrier
	s_and_saveexec_b64 s[8:9], vcc
	s_cbranch_execnz .LBB0_772
	s_or_b64 exec, exec, s[8:9]
	v_cmp_lt_i32_e32 vcc, 1, v156
	s_and_saveexec_b64 s[8:9], vcc
	s_cbranch_execnz .LBB0_773

.LBB0_692:
	s_or_b64 exec, exec, s[8:9]
	v_lshlrev_b32_e32 v153, 14, v153
	v_lshlrev_b32_e32 v154, 2, v154
	v_add3_u32 v153, 0, v153, v154
	v_fmac_f32_e32 v117, v116, v152
	v_lshl_add_u32 v116, v155, 8, v153
	ds_write_b32 v176, v117 offset:58368
	v_fmac_f32_e32 v119, v118, v117
	v_lshl_add_u32 v116, v157, 8, v153
	ds_write_b32 v177, v119 offset:58368
	v_fmac_f32_e32 v121, v120, v119
	v_lshl_add_u32 v116, v158, 8, v153
	ds_write_b32 v178, v121 offset:58368
	v_fmac_f32_e32 v123, v122, v121
	v_lshl_add_u32 v116, v159, 8, v153
	ds_write_b32 v179, v123 offset:58368
	v_fmac_f32_e32 v125, v124, v123
	v_lshl_add_u32 v116, v160, 8, v153
	ds_write_b32 v180, v125 offset:58368
	v_fmac_f32_e32 v127, v126, v125
	v_lshl_add_u32 v116, v161, 8, v153
	ds_write_b32 v181, v127 offset:58368
	v_fmac_f32_e32 v129, v128, v127
	v_lshl_add_u32 v116, v162, 8, v153
	ds_write_b32 v182, v129 offset:58368
	v_fmac_f32_e32 v131, v130, v129
	v_lshl_add_u32 v116, v163, 8, v153
	ds_write_b32 v183, v131 offset:58368
	v_fmac_f32_e32 v133, v132, v131
	v_lshl_add_u32 v116, v164, 8, v153
	ds_write_b32 v184, v133 offset:58368
	v_fmac_f32_e32 v135, v134, v133
	v_lshl_add_u32 v116, v165, 8, v153
	ds_write_b32 v185, v135 offset:58368
	v_fmac_f32_e32 v137, v136, v135
	v_lshl_add_u32 v116, v166, 8, v153
	ds_write_b32 v186, v137 offset:58368
	v_fmac_f32_e32 v139, v138, v137
	v_lshl_add_u32 v116, v167, 8, v153
	ds_write_b32 v187, v139 offset:58368
	v_fmac_f32_e32 v141, v140, v139
	v_lshl_add_u32 v116, v168, 8, v153
	ds_write_b32 v188, v141 offset:58368
	v_fmac_f32_e32 v143, v142, v141
	v_lshl_add_u32 v116, v169, 8, v153
	ds_write_b32 v189, v143 offset:58368
	v_fmac_f32_e32 v145, v144, v143
	v_lshl_add_u32 v116, v170, 8, v153
	ds_write_b32 v190, v145 offset:58368
	v_fmac_f32_e32 v147, v146, v145
	v_lshl_add_u32 v116, v171, 8, v153
	v_lshlrev_b32_e32 v132, 16, v100
	ds_write_b32 v191, v147 offset:58368
	v_mul_f32_e32 v116, 0x3d372713, v132
	v_mul_f32_e32 v116, v116, v132
	v_mov_b32_e32 v117, v132
	v_fmac_f32_e32 v117, v116, v117
	v_mul_f32_e32 v116, 0x3f4c422a, v117
	v_lshlrev_b32_e32 v117, 2, v1
	v_and_b32_e32 v133, 0xffff0000, v100
	v_add3_u32 v128, v151, v117, s46
	v_mul_f32_e32 v117, 0x3d372713, v133
	v_mul_f32_e32 v117, v117, v133
	v_mov_b32_e32 v118, v133
	v_fmac_f32_e32 v118, v117, v118
	v_add_f32_e32 v116, v116, v116
	v_mul_f32_e32 v117, 0x3f4c422a, v118
	v_mul_f32_e32 v116, 0x3fb8aa3b, v116
	v_add_f32_e32 v117, v117, v117
	v_exp_f32_e32 v116, v116
	v_mul_f32_e32 v117, 0x3fb8aa3b, v117
	v_exp_f32_e32 v124, v117
	s_waitcnt lgkmcnt(0)
	v_add_f32_e32 v116, 1.0, v116
	s_barrier
	v_lshlrev_b32_e32 v196, 1, v204
	v_and_b32_e32 v196, 0x30, v196
	v_xor_b32_e32 v197, v196, v3
	v_xor_b32_e32 v198, 16, v197
	v_xor_b32_e32 v199, v196, v128
	v_xor_b32_e32 v202, 16, v199
	v_rcp_f32_e32 v134, v116
	ds_read_b128 v[116:119], v197 offset:58368
	ds_read_b128 v[120:123], v199 offset:16384
	v_add_f32_e32 v124, 1.0, v124
	v_rcp_f32_e32 v135, v124
	ds_read_b128 v[124:127], v198 offset:58368
	ds_read_b128 v[128:131], v202 offset:16384
	v_pk_mul_f32 v[132:133], v[132:133], 0.5 op_sel_hi:[1,0]
	s_waitcnt lgkmcnt(2)
	v_pk_add_f32 v[116:117], v[116:117], v[120:121]
	v_pk_fma_f32 v[120:121], v[134:135], 2.0, 1.0 op_sel_hi:[1,0,0] neg_lo:[1,0,0] neg_hi:[1,0,0]
	v_lshlrev_b32_e32 v134, 16, v101
	v_mul_f32_e32 v3, 0x3d372713, v134
	v_mul_f32_e32 v3, v3, v134
	v_mov_b32_e32 v136, v134
	v_and_b32_e32 v135, 0xffff0000, v101
	v_fmac_f32_e32 v136, v3, v136
	v_mul_f32_e32 v3, 0x3f4c422a, v136
	v_mul_f32_e32 v136, 0x3d372713, v135
	v_mul_f32_e32 v136, v136, v135
	v_mov_b32_e32 v137, v135
	v_fmac_f32_e32 v137, v136, v137
	v_add_f32_e32 v3, v3, v3
	v_mul_f32_e32 v136, 0x3f4c422a, v137
	v_mul_f32_e32 v3, 0x3fb8aa3b, v3
	v_add_f32_e32 v136, v136, v136
	v_exp_f32_e32 v3, v3
	v_mul_f32_e32 v136, 0x3fb8aa3b, v136
	v_exp_f32_e32 v137, v136
	v_pk_add_f32 v[120:121], v[120:121], 1.0 op_sel_hi:[1,0]
	v_add_f32_e32 v3, 1.0, v3
	v_rcp_f32_e32 v136, v3
	v_add_f32_e32 v3, 1.0, v137
	v_pk_mul_f32 v[120:121], v[132:133], v[120:121]
	v_lshlrev_b32_e32 v132, 16, v102
	v_rcp_f32_e32 v137, v3
	v_mul_f32_e32 v3, 0x3d372713, v132
	v_pk_add_f32 v[118:119], v[118:119], v[122:123]
	v_pk_mul_f32 v[122:123], v[134:135], 0.5 op_sel_hi:[1,0]
	v_mul_f32_e32 v3, v3, v132
	v_mov_b32_e32 v134, v132
	v_and_b32_e32 v133, 0xffff0000, v102
	v_fmac_f32_e32 v134, v3, v134
	v_mul_f32_e32 v3, 0x3f4c422a, v134
	v_mul_f32_e32 v134, 0x3d372713, v133
	v_mul_f32_e32 v134, v134, v133
	v_mov_b32_e32 v135, v133
	v_fmac_f32_e32 v135, v134, v135
	v_add_f32_e32 v3, v3, v3
	v_mul_f32_e32 v134, 0x3f4c422a, v135
	v_mul_f32_e32 v3, 0x3fb8aa3b, v3
	v_add_f32_e32 v134, v134, v134
	v_exp_f32_e32 v3, v3
	v_mul_f32_e32 v134, 0x3fb8aa3b, v134
	v_exp_f32_e32 v135, v134
	v_pk_mul_f32 v[116:117], v[120:121], v[116:117]
	v_pk_fma_f32 v[120:121], v[136:137], 2.0, 1.0 op_sel_hi:[1,0,0] neg_lo:[1,0,0] neg_hi:[1,0,0]
	v_add_f32_e32 v3, 1.0, v3
	v_pk_add_f32 v[120:121], v[120:121], 1.0 op_sel_hi:[1,0]
	v_rcp_f32_e32 v134, v3
	v_pk_mul_f32 v[120:121], v[122:123], v[120:121]
	v_add_f32_e32 v3, 1.0, v135
	v_pk_mul_f32 v[118:119], v[120:121], v[118:119]
	s_waitcnt lgkmcnt(0)
	v_pk_add_f32 v[120:121], v[124:125], v[128:129]
	v_lshlrev_b32_e32 v128, 16, v103
	v_rcp_f32_e32 v135, v3
	v_mul_f32_e32 v3, 0x3d372713, v128
	v_pk_mul_f32 v[124:125], v[132:133], 0.5 op_sel_hi:[1,0]
	v_mul_f32_e32 v3, v3, v128
	v_mov_b32_e32 v132, v128
	v_and_b32_e32 v129, 0xffff0000, v103
	v_fmac_f32_e32 v132, v3, v132
	v_mul_f32_e32 v3, 0x3f4c422a, v132
	v_mul_f32_e32 v132, 0x3d372713, v129
	v_mul_f32_e32 v132, v132, v129
	v_mov_b32_e32 v133, v129
	v_fmac_f32_e32 v133, v132, v133
	v_add_f32_e32 v3, v3, v3
	v_mul_f32_e32 v132, 0x3f4c422a, v133
	v_mul_f32_e32 v3, 0x3fb8aa3b, v3
	v_add_f32_e32 v132, v132, v132
	v_exp_f32_e32 v3, v3
	v_mul_f32_e32 v132, 0x3fb8aa3b, v132
	v_exp_f32_e32 v133, v132
	s_ashr_i32 s8, s2, 9
	v_add_f32_e32 v3, 1.0, v3
	v_rcp_f32_e32 v132, v3
	v_add_f32_e32 v3, 1.0, v133
	v_rcp_f32_e32 v133, v3
	v_pk_fma_f32 v[122:123], v[134:135], 2.0, 1.0 op_sel_hi:[1,0,0] neg_lo:[1,0,0] neg_hi:[1,0,0]
	s_ashr_i32 s9, s8, 31
	v_pk_add_f32 v[122:123], v[122:123], 1.0 op_sel_hi:[1,0]
	s_lshl_b64 s[8:9], s[8:9], 12
	s_and_b32 s10, s12, 0xfc0
	v_pk_mul_f32 v[122:123], v[124:125], v[122:123]
	v_pk_fma_f32 v[124:125], v[132:133], 2.0, 1.0 op_sel_hi:[1,0,0] neg_lo:[1,0,0] neg_hi:[1,0,0]
	s_or_b32 s8, s8, s10
	v_ashrrev_i32_e32 v3, 31, v2
	v_pk_mul_f32 v[120:121], v[122:123], v[120:121]
	v_pk_add_f32 v[122:123], v[126:127], v[130:131]
	v_pk_mul_f32 v[126:127], v[128:129], 0.5 op_sel_hi:[1,0]
	v_pk_add_f32 v[124:125], v[124:125], 1.0 op_sel_hi:[1,0]
	v_lshl_add_u64 v[2:3], s[8:9], 0, v[2:3]
	s_and_b32 s8, s13, 0x1c0
	v_pk_mul_f32 v[124:125], v[126:127], v[124:125]
	v_or_b32_e32 v1, s8, v1
	v_lshlrev_b64 v[2:3], 11, v[2:3]
	v_pk_mul_f32 v[122:123], v[124:125], v[122:123]
	v_cvt_pk_bf16_f32 v116, v116, v117
	v_cvt_pk_bf16_f32 v117, v118, v119
	v_cvt_pk_bf16_f32 v118, v120, v121
	v_lshl_add_u64 v[2:3], s[16:17], 0, v[2:3]
	v_lshlrev_b32_e32 v120, 1, v1
	v_mov_b32_e32 v121, v0
	v_cvt_pk_bf16_f32 v119, v122, v123
	v_lshl_add_u64 v[2:3], v[2:3], 0, v[120:121]
	s_cmpk_gt_i32 s50, 0xfff
	s_mov_b64 s[8:9], -1
	s_waitcnt vmcnt(0)
	global_store_dwordx4 v[2:3], v[116:119], off
	s_nop 0
	s_cbranch_scc1 .LBB0_611
	s_add_i32 s2, s89, s2
	s_cmpk_gt_i32 s2, 0xfff
	s_cbranch_scc1 .LBB0_703
	v_mov_b32_e32 v118, v204
	s_ashr_i32 s8, s2, 9
	s_bfe_u32 s2, s2, 0x60003
	s_add_i32 s9, s88, s13
	s_and_b32 s61, s9, 0x1c0
	v_ashrrev_i32_e32 v102, 3, v118
	v_lshlrev_b32_e32 v1, 3, v118
	s_lshl_b32 s62, s2, 6
	v_and_or_b32 v2, v1, 56, s61
	v_add_u32_e32 v60, s62, v102
	v_mov_b32_e32 v30, v0
	v_mov_b32_e32 v31, v0
	v_add_u32_e32 v1, -2, v60
	v_lshlrev_b32_e32 v100, 1, v2
	v_mov_b32_e32 v101, v0
	v_mov_b32_e32 v28, v0
	v_mov_b32_e32 v29, v0
	v_mov_b64_e32 v[42:43], v[30:31]
	s_lshl_b32 s9, s8, 12
	v_lshl_add_u64 v[116:117], s[66:67], 0, v[100:101]
	v_cmp_gt_u32_e32 vcc, s48, v1
	v_mov_b64_e32 v[40:41], v[28:29]
	s_and_saveexec_b64 s[10:11], vcc
	s_cbranch_execz .LBB0_696
	v_or_b32_e32 v1, s9, v1
	v_mad_i64_i32 v[2:3], s[64:65], v1, s0, v[116:117]
	global_load_dwordx4 v[40:43], v[2:3], off

.LBB0_705:
	v_lshlrev_b32_e32 v2, 16, v68
	v_and_b32_e32 v3, 0xffff0000, v68
	s_nop 0
	v_pk_fma_f32 v[2:3], v[36:37], v[2:3], v[48:49]
	v_lshlrev_b32_e32 v116, 16, v96
	v_and_b32_e32 v117, 0xffff0000, v96
	v_pk_fma_f32 v[2:3], v[8:9], v[116:117], v[2:3]
	v_lshlrev_b32_e32 v116, 16, v104
	v_and_b32_e32 v117, 0xffff0000, v104
	v_pk_fma_f32 v[2:3], v[12:13], v[116:117], v[2:3]
	v_lshlrev_b32_e32 v116, 16, v108
	v_and_b32_e32 v117, 0xffff0000, v108
	v_pk_fma_f32 v[116:117], v[16:17], v[116:117], v[2:3]
	v_lshlrev_b32_e32 v2, 16, v70
	v_and_b32_e32 v3, 0xffff0000, v70
	v_pk_fma_f32 v[2:3], v[24:25], v[2:3], v[44:45]
	v_lshlrev_b32_e32 v118, 16, v98
	v_and_b32_e32 v119, 0xffff0000, v98
	v_pk_fma_f32 v[2:3], v[4:5], v[118:119], v[2:3]
	v_lshlrev_b32_e32 v118, 16, v106
	v_and_b32_e32 v119, 0xffff0000, v106
	v_pk_fma_f32 v[2:3], v[20:21], v[118:119], v[2:3]
	v_lshlrev_b32_e32 v118, 16, v110
	v_and_b32_e32 v119, 0xffff0000, v110
	v_pk_fma_f32 v[120:121], v[32:33], v[118:119], v[2:3]
	v_lshlrev_b32_e32 v2, 16, v69
	v_and_b32_e32 v3, 0xffff0000, v69
	v_pk_fma_f32 v[2:3], v[38:39], v[2:3], v[50:51]
	v_lshlrev_b32_e32 v118, 16, v97
	v_and_b32_e32 v119, 0xffff0000, v97
	v_pk_fma_f32 v[2:3], v[10:11], v[118:119], v[2:3]
	v_lshlrev_b32_e32 v118, 16, v105
	v_and_b32_e32 v119, 0xffff0000, v105
	v_pk_fma_f32 v[2:3], v[14:15], v[118:119], v[2:3]
	v_lshlrev_b32_e32 v118, 16, v109
	v_and_b32_e32 v119, 0xffff0000, v109
	v_pk_fma_f32 v[118:119], v[18:19], v[118:119], v[2:3]
	v_lshlrev_b32_e32 v2, 16, v71
	v_and_b32_e32 v3, 0xffff0000, v71
	v_pk_fma_f32 v[2:3], v[26:27], v[2:3], v[46:47]
	v_lshlrev_b32_e32 v122, 16, v99
	v_and_b32_e32 v123, 0xffff0000, v99
	v_pk_fma_f32 v[2:3], v[6:7], v[122:123], v[2:3]
	v_lshlrev_b32_e32 v122, 16, v107
	v_and_b32_e32 v123, 0xffff0000, v107
	v_mov_b32_e32 v152, v204
	v_pk_fma_f32 v[2:3], v[22:23], v[122:123], v[2:3]
	v_lshlrev_b32_e32 v122, 16, v111
	v_and_b32_e32 v123, 0xffff0000, v111
	v_pk_fma_f32 v[122:123], v[34:35], v[122:123], v[2:3]
	v_lshlrev_b32_e32 v1, 3, v152
	v_ashrrev_i32_e32 v2, 3, v152
	v_and_b32_e32 v1, 56, v1
	v_lshl_add_u32 v151, v2, 8, 0
	v_lshl_add_u32 v3, v1, 2, v151
	ds_write_b128 v3, v[116:119]
	ds_write_b128 v3, v[120:123] offset:16
	v_cvt_pk_bf16_f32 v116, v116, v117
	v_cvt_pk_bf16_f32 v117, v118, v119
	v_cvt_pk_bf16_f32 v118, v120, v121
	v_mul_lo_u32 v120, v2, s1
	v_lshlrev_b32_e32 v121, 1, v1
	v_and_b32_e32 v162, 15, v152
	v_cvt_pk_bf16_f32 v119, v122, v123
	v_add3_u32 v120, v151, v120, v121
	v_and_b32_e32 v153, 48, v152
	ds_write_b128 v120, v[116:119] offset:16384
	v_mul_u32_u24_e32 v116, 0x90, v162
	v_add3_u32 v163, 0, v153, v116
	s_waitcnt lgkmcnt(0)
	s_barrier
	ds_read_b128 v[128:131], v163 offset:20992
	s_waitcnt lgkmcnt(0)
	v_mfma_f32_16x16x32_bf16 v[136:139], v[56:59], v[128:131], 0
	ds_read_b128 v[116:119], v163 offset:16384
	ds_read_b128 v[124:127], v163 offset:18688
	v_cmp_gt_u32_e32 vcc, s49, v152
	s_nop 0
	v_mfma_f32_16x16x32_bf16 v[140:143], v[72:75], v[128:131], 0
	ds_read_b128 v[128:131], v163 offset:23296
	s_waitcnt lgkmcnt(0)
	v_mfma_f32_16x16x32_bf16 v[144:147], v[56:59], v[128:131], 0
	v_mfma_f32_16x16x32_bf16 v[154:157], v[72:75], v[128:131], 0
	ds_read_b128 v[128:131], v163 offset:16448
	v_mfma_f32_16x16x32_bf16 v[120:123], v[56:59], v[116:119], 0
	v_mfma_f32_16x16x32_bf16 v[116:119], v[72:75], v[116:119], 0
	s_waitcnt lgkmcnt(0)
	v_mfma_f32_16x16x32_bf16 v[158:161], v[64:67], v[128:131], v[120:123]
	s_nop 0
	v_mfma_f32_16x16x32_bf16 v[128:131], v[76:79], v[128:131], v[116:119]
	s_nop 3
	ds_read_b128 v[116:119], v163 offset:18752
	v_mfma_f32_16x16x32_bf16 v[132:135], v[56:59], v[124:127], 0
	s_nop 0
	s_nop 0
	v_add_f32_e32 v128, v84, v128
	v_mul_f32_e32 v128, 0xbfb8aa3b, v128
	v_exp_f32_e32 v128, v128
	v_mfma_f32_16x16x32_bf16 v[124:127], v[72:75], v[124:127], 0
	v_add_f32_e32 v129, v85, v129
	v_mul_f32_e32 v129, 0xbfb8aa3b, v129
	v_exp_f32_e32 v129, v129
	s_waitcnt lgkmcnt(0)
	v_mfma_f32_16x16x32_bf16 v[132:135], v[64:67], v[116:119], v[132:135]
	v_add_f32_e32 v130, v86, v130
	v_mul_f32_e32 v130, 0xbfb8aa3b, v130
	v_add_f32_e32 v128, 1.0, v128
	v_mfma_f32_16x16x32_bf16 v[124:127], v[76:79], v[116:119], v[124:127]
	ds_read_b128 v[116:119], v163 offset:21056
	s_nop 2
	v_add_f32_e32 v132, v80, v132
	v_mul_f32_e32 v132, 0xbfb8aa3b, v132
	s_waitcnt lgkmcnt(0)
	v_mfma_f32_16x16x32_bf16 v[136:139], v[64:67], v[116:119], v[136:139]
	v_exp_f32_e32 v132, v132
	v_add_f32_e32 v133, v81, v133
	v_mul_f32_e32 v133, 0xbfb8aa3b, v133
	v_mfma_f32_16x16x32_bf16 v[120:123], v[76:79], v[116:119], v[140:143]
	ds_read_b128 v[116:119], v163 offset:23360
	v_exp_f32_e32 v133, v133
	v_add_f32_e32 v134, v82, v134
	s_waitcnt lgkmcnt(0)
	v_mfma_f32_16x16x32_bf16 v[140:143], v[64:67], v[116:119], v[144:147]
	v_mul_f32_e32 v134, 0xbfb8aa3b, v134
	s_nop 1
	v_mov_b32_e32 v144, s51
	v_mov_b32_e32 v145, s81
	v_cndmask_b32_e32 v144, v144, v145, vcc
	v_lshlrev_b32_e32 v145, 7, v152
	v_and_b32_e32 v145, 0x4000, v145
	v_lshlrev_b32_e32 v146, 8, v162
	v_add3_u32 v144, v144, v145, v146
	v_add_f32_e32 v146, v80, v158
	v_mul_f32_e32 v146, 0xbfb8aa3b, v146
	v_add_f32_e32 v147, v81, v159
	v_exp_f32_e32 v146, v146
	v_mul_f32_e32 v147, 0xbfb8aa3b, v147
	v_exp_f32_e32 v147, v147
	v_lshlrev_b32_e32 v145, 1, v152
	v_and_b32_e32 v145, 0x80, v145
	v_add_f32_e32 v146, 1.0, v146
	v_rcp_f32_e32 v146, v146
	v_add3_u32 v153, v144, v145, v153
	v_xor_b32_e32 v153, v201, v153
	v_add_f32_e32 v144, 1.0, v147
	v_add_f32_e32 v147, v82, v160
	v_mul_f32_e32 v147, 0xbfb8aa3b, v147
	v_mfma_f32_16x16x32_bf16 v[116:119], v[76:79], v[116:119], v[154:157]
	v_rcp_f32_e32 v145, v144
	v_exp_f32_e32 v147, v147

	s_nop 0
	v_add_f32_e32 v154, v83, v161
	v_mul_f32_e32 v154, 0xbfb8aa3b, v154
	v_exp_f32_e32 v154, v154
	s_nop 0

	v_mul_f32_e32 v144, v240, v146

	v_add_f32_e32 v147, 1.0, v147

	v_rcp_f32_e32 v147, v147
	v_mul_f32_e32 v145, v241, v145
	v_add_f32_e32 v146, 1.0, v154
	v_rcp_f32_e32 v154, v146

	v_add_f32_e32 v132, 1.0, v132
	v_exp_f32_e32 v134, v134
	v_add_f32_e32 v135, v83, v135

	v_rcp_f32_e32 v132, v132
	v_mul_f32_e32 v135, 0xbfb8aa3b, v135
	v_mul_f32_e32 v146, v242, v147

	v_add_f32_e32 v133, 1.0, v133
	v_exp_f32_e32 v135, v135

	v_rcp_f32_e32 v133, v133
	v_mul_f32_e32 v147, v243, v154
	v_add_f32_e32 v134, 1.0, v134
	v_add_f32_e32 v136, v80, v136
	ds_write_b128 v153, v[144:147]

	v_rcp_f32_e32 v134, v134
	v_mul_f32_e32 v136, 0xbfb8aa3b, v136

	v_add_f32_e32 v135, 1.0, v135
	v_exp_f32_e32 v136, v136
	v_mul_f32_e32 v132, v240, v132

	v_rcp_f32_e32 v135, v135

	v_add_f32_e32 v137, v81, v137
	v_mul_f32_e32 v133, v241, v133

	v_mul_f32_e32 v137, 0xbfb8aa3b, v137

	v_exp_f32_e32 v137, v137
	v_add_f32_e32 v136, 1.0, v136
	v_mul_f32_e32 v134, v242, v134

	v_rcp_f32_e32 v136, v136

	v_mul_f32_e32 v135, v243, v135
	ds_write_b128 v153, v[132:135] offset:4096
	v_add_f32_e32 v132, 1.0, v137
	v_rcp_f32_e32 v133, v132

	v_add_f32_e32 v135, v82, v138

	v_mul_f32_e32 v135, 0xbfb8aa3b, v135
	v_mul_f32_e32 v132, v240, v136
	v_exp_f32_e32 v135, v135
	v_add_f32_e32 v136, v83, v139
	v_mul_f32_e32 v136, 0xbfb8aa3b, v136
	v_exp_f32_e32 v136, v136

	v_add_f32_e32 v135, 1.0, v135

	v_rcp_f32_e32 v135, v135
	v_mul_f32_e32 v133, v241, v133
	v_add_f32_e32 v134, 1.0, v136
	v_rcp_f32_e32 v136, v134


	v_mul_f32_e32 v134, v242, v135


	v_mul_f32_e32 v135, v243, v136
	v_add_f32_e32 v136, v80, v140
	v_mul_f32_e32 v136, 0xbfb8aa3b, v136
	v_exp_f32_e32 v136, v136
	v_add_f32_e32 v137, v81, v141
	v_mul_f32_e32 v137, 0xbfb8aa3b, v137
	v_exp_f32_e32 v137, v137
	v_add_f32_e32 v136, 1.0, v136
	v_rcp_f32_e32 v136, v136
	ds_write_b128 v153, v[132:135] offset:8192
	v_add_f32_e32 v132, 1.0, v137
	v_rcp_f32_e32 v133, v132

	v_add_f32_e32 v135, v82, v142

	v_mul_f32_e32 v135, 0xbfb8aa3b, v135
	v_mul_f32_e32 v132, v240, v136
	v_exp_f32_e32 v135, v135
	v_add_f32_e32 v136, v83, v143
	v_mul_f32_e32 v136, 0xbfb8aa3b, v136
	v_exp_f32_e32 v136, v136

	v_add_f32_e32 v135, 1.0, v135

	v_rcp_f32_e32 v135, v135
	v_mul_f32_e32 v133, v241, v133
	v_add_f32_e32 v134, 1.0, v136
	v_rcp_f32_e32 v136, v134

	v_exp_f32_e32 v130, v130
	v_add_f32_e32 v131, v87, v131

	v_rcp_f32_e32 v128, v128
	v_mul_f32_e32 v131, 0xbfb8aa3b, v131
	v_mul_f32_e32 v134, v242, v135

	v_add_f32_e32 v129, 1.0, v129
	v_exp_f32_e32 v131, v131

	v_rcp_f32_e32 v129, v129
	v_add_f32_e32 v124, v84, v124
	v_mul_f32_e32 v135, v243, v136
	v_add_f32_e32 v130, 1.0, v130
	v_mul_f32_e32 v124, 0xbfb8aa3b, v124
	ds_write_b128 v153, v[132:135] offset:12288

	v_rcp_f32_e32 v130, v130
	v_exp_f32_e32 v124, v124
	v_add_f32_e32 v125, v85, v125
	s_nop 0

	v_add_f32_e32 v131, 1.0, v131
	v_mul_f32_e32 v125, 0xbfb8aa3b, v125
	v_mul_f32_e32 v128, v244, v128

	v_rcp_f32_e32 v131, v131
	v_exp_f32_e32 v125, v125
	v_add_f32_e32 v126, v86, v126

	v_mul_f32_e32 v126, 0xbfb8aa3b, v126
	v_mul_f32_e32 v129, v245, v129

	v_add_f32_e32 v124, 1.0, v124
	v_exp_f32_e32 v126, v126
	v_add_f32_e32 v127, v87, v127

	v_rcp_f32_e32 v124, v124
	v_mul_f32_e32 v127, 0xbfb8aa3b, v127
	v_mul_f32_e32 v130, v246, v130

	v_add_f32_e32 v125, 1.0, v125
	v_exp_f32_e32 v127, v127

	v_rcp_f32_e32 v125, v125
	v_add_f32_e32 v120, v84, v120
	v_mul_f32_e32 v131, v247, v131
	v_add_f32_e32 v126, 1.0, v126
	v_mul_f32_e32 v120, 0xbfb8aa3b, v120
	ds_write_b128 v153, v[128:131] offset:64

	v_rcp_f32_e32 v126, v126
	v_exp_f32_e32 v120, v120
	v_add_f32_e32 v121, v85, v121

	v_add_f32_e32 v127, 1.0, v127
	v_mul_f32_e32 v121, 0xbfb8aa3b, v121
	v_mul_f32_e32 v124, v244, v124

	v_rcp_f32_e32 v127, v127
	v_exp_f32_e32 v121, v121
	v_add_f32_e32 v122, v86, v122

	v_mul_f32_e32 v122, 0xbfb8aa3b, v122
	v_mul_f32_e32 v125, v245, v125

	v_add_f32_e32 v120, 1.0, v120
	v_exp_f32_e32 v122, v122
	v_add_f32_e32 v123, v87, v123

	v_rcp_f32_e32 v120, v120
	v_mul_f32_e32 v123, 0xbfb8aa3b, v123
	v_mul_f32_e32 v126, v246, v126

	v_add_f32_e32 v121, 1.0, v121
	v_exp_f32_e32 v123, v123

	v_rcp_f32_e32 v121, v121
	v_add_f32_e32 v116, v84, v116
	v_mul_f32_e32 v127, v247, v127
	v_add_f32_e32 v122, 1.0, v122
	v_mul_f32_e32 v116, 0xbfb8aa3b, v116
	ds_write_b128 v153, v[124:127] offset:4160

	v_rcp_f32_e32 v122, v122
	v_exp_f32_e32 v116, v116
	v_add_f32_e32 v117, v85, v117

	v_add_f32_e32 v123, 1.0, v123
	v_mul_f32_e32 v117, 0xbfb8aa3b, v117
	v_mul_f32_e32 v120, v244, v120

	v_rcp_f32_e32 v123, v123
	v_exp_f32_e32 v117, v117
	v_add_f32_e32 v118, v86, v118

	v_mul_f32_e32 v118, 0xbfb8aa3b, v118
	v_mul_f32_e32 v121, v245, v121

	v_add_f32_e32 v116, 1.0, v116
	v_exp_f32_e32 v118, v118
	v_add_f32_e32 v119, v87, v119

	v_rcp_f32_e32 v116, v116
	v_mul_f32_e32 v119, 0xbfb8aa3b, v119
	v_mul_f32_e32 v122, v246, v122

	v_add_f32_e32 v117, 1.0, v117
	v_exp_f32_e32 v119, v119

	v_rcp_f32_e32 v117, v117
	v_mul_f32_e32 v123, v247, v123
	v_add_f32_e32 v118, 1.0, v118
	ds_write_b128 v153, v[120:123] offset:8256

	v_rcp_f32_e32 v118, v118

	v_add_f32_e32 v119, 1.0, v119
	v_mul_f32_e32 v116, v244, v116

	v_rcp_f32_e32 v119, v119

	v_mul_f32_e32 v117, v245, v117


	v_mul_f32_e32 v118, v246, v118


	v_mul_f32_e32 v119, v247, v119
	v_lshlrev_b32_e32 v133, 2, v152
	ds_write_b128 v153, v[116:119] offset:12352
	v_and_b32_e32 v116, 60, v133
	v_lshlrev_b32_e32 v132, 2, v116
	v_lshlrev_b32_e32 v116, 4, v152
	v_and_b32_e32 v117, 0xffffc000, v116
	v_add_u32_e32 v117, 0, v117
	v_and_b32_e32 v116, 0x3f00, v116
	v_add3_u32 v135, v117, v116, v132
	v_xor_b32_e32 v135, v200, v135
	s_waitcnt lgkmcnt(0)
	s_barrier
	ds_read_b128 v[128:131], v135 offset:25600
	ds_read_b128 v[120:123], v135 offset:58368
	v_add_u32_e32 v134, 0, v132
	v_add_u32_e32 v136, v134, v116
	ds_read_b128 v[124:127], v136
	s_waitcnt lgkmcnt(2)
	v_mul_f32_e32 v116, 0x3fb8aa3b, v128
	v_exp_f32_e32 v116, v116
	v_add_f32_e32 v117, v128, v128
	v_cmp_nlt_f32_e32 vcc, s79, v117
	s_and_saveexec_b64 s[6:7], vcc
	s_xor_b64 s[6:7], exec, s[6:7]
	v_fma_f32 v128, -v116, v116, 1.0
	s_andn2_saveexec_b64 s[6:7], s[6:7]
	v_fmamk_f32 v118, v117, 0x3c088889, v148
	v_fmaak_f32 v118, v117, v118, 0x3e2aaaab
	v_fma_f32 v118, v117, v118, 0.5
	v_fma_f32 v118, v117, v118, 1.0
	v_mul_f32_e64 v128, v118, -v117
	s_or_b64 exec, exec, s[6:7]
	v_mul_f32_e32 v117, 0x3fb8aa3b, v129
	v_exp_f32_e32 v117, v117
	v_add_f32_e32 v118, v129, v129
	v_cmp_nlt_f32_e32 vcc, s79, v118
	s_and_saveexec_b64 s[6:7], vcc
	s_xor_b64 s[6:7], exec, s[6:7]
	v_fma_f32 v129, -v117, v117, 1.0
	s_andn2_saveexec_b64 s[6:7], s[6:7]
	v_fmamk_f32 v119, v118, 0x3c088889, v148
	v_fmaak_f32 v119, v118, v119, 0x3e2aaaab
	v_fma_f32 v119, v118, v119, 0.5
	v_fma_f32 v119, v118, v119, 1.0
	v_mul_f32_e64 v129, v119, -v118
	s_or_b64 exec, exec, s[6:7]
	v_mul_f32_e32 v118, 0x3fb8aa3b, v130
	v_exp_f32_e32 v118, v118
	v_add_f32_e32 v119, v130, v130
	v_cmp_nlt_f32_e32 vcc, s79, v119
	s_and_saveexec_b64 s[6:7], vcc
	s_xor_b64 s[6:7], exec, s[6:7]
	v_fma_f32 v130, -v118, v118, 1.0
	s_andn2_saveexec_b64 s[6:7], s[6:7]
	v_fmamk_f32 v130, v119, 0x3c088889, v148
	v_fmaak_f32 v130, v119, v130, 0x3e2aaaab
	v_fma_f32 v130, v119, v130, 0.5
	v_fma_f32 v130, v119, v130, 1.0
	v_mul_f32_e64 v130, v130, -v119
	s_or_b64 exec, exec, s[6:7]
	v_mul_f32_e32 v119, 0x3fb8aa3b, v131
	v_exp_f32_e32 v119, v119
	v_add_f32_e32 v137, v131, v131
	v_cmp_nlt_f32_e32 vcc, s79, v137
	s_and_saveexec_b64 s[6:7], vcc
	s_xor_b64 s[6:7], exec, s[6:7]
	v_fma_f32 v131, -v119, v119, 1.0
	s_andn2_saveexec_b64 s[6:7], s[6:7]
	v_fmamk_f32 v131, v137, 0x3c088889, v148
	v_fmaak_f32 v131, v137, v131, 0x3e2aaaab
	v_fma_f32 v131, v137, v131, 0.5
	v_fma_f32 v131, v137, v131, 1.0
	v_mul_f32_e64 v131, v131, -v137
	s_or_b64 exec, exec, s[6:7]
	v_max_f32_e32 v128, v128, v128
	v_max_f32_e32 v128, 0, v128
	v_sqrt_f32_e32 v128, v128
	v_max_f32_e32 v129, v129, v129
	v_max_f32_e32 v129, 0, v129
	v_sqrt_f32_e32 v129, v129
	s_waitcnt lgkmcnt(1)
	v_mul_f32_e32 v120, v120, v128
	s_waitcnt lgkmcnt(0)
	v_mul_f32_e32 v120, v124, v120
	v_max_f32_e32 v124, v130, v130
	v_max_f32_e32 v128, v131, v131
	v_max_f32_e32 v124, 0, v124
	v_max_f32_e32 v128, 0, v128
	v_sqrt_f32_e32 v124, v124
	v_sqrt_f32_e32 v128, v128
	v_mul_f32_e32 v121, v121, v129
	v_mul_f32_e32 v121, v125, v121
	v_mul_f32_e32 v122, v122, v124
	v_mul_f32_e32 v123, v123, v128
	v_mul_f32_e32 v122, v126, v122
	v_mul_f32_e32 v123, v127, v123
	ds_write_b128 v135, v[116:119] offset:25600
	ds_write_b128 v135, v[120:123] offset:58368
	v_add_u32_e32 v116, 0x800, v133
	v_and_b32_e32 v117, 0x3ffff000, v116
	v_and_b32_e32 v116, 0xfc0, v116
	v_lshl_add_u32 v117, v117, 2, 0
	v_lshlrev_b32_e32 v116, 2, v116
	v_add3_u32 v137, v117, v116, v132
	v_xor_b32_e32 v137, v200, v137
	ds_read_b128 v[128:131], v137 offset:25600
	ds_read_b128 v[120:123], v137 offset:58368
	v_add_u32_e32 v116, v134, v116
	ds_read_b128 v[124:127], v116
	s_waitcnt lgkmcnt(2)
	v_mul_f32_e32 v116, 0x3fb8aa3b, v128
	v_exp_f32_e32 v116, v116
	v_add_f32_e32 v117, v128, v128
	v_cmp_nlt_f32_e32 vcc, s79, v117
	s_and_saveexec_b64 s[6:7], vcc
	s_xor_b64 s[6:7], exec, s[6:7]
	v_fma_f32 v128, -v116, v116, 1.0
	s_andn2_saveexec_b64 s[6:7], s[6:7]
	v_fmamk_f32 v118, v117, 0x3c088889, v148
	v_fmaak_f32 v118, v117, v118, 0x3e2aaaab
	v_fma_f32 v118, v117, v118, 0.5
	v_fma_f32 v118, v117, v118, 1.0
	v_mul_f32_e64 v128, v118, -v117
	s_or_b64 exec, exec, s[6:7]
	v_mul_f32_e32 v117, 0x3fb8aa3b, v129
	v_exp_f32_e32 v117, v117
	v_add_f32_e32 v118, v129, v129
	v_cmp_nlt_f32_e32 vcc, s79, v118
	s_and_saveexec_b64 s[6:7], vcc
	s_xor_b64 s[6:7], exec, s[6:7]
	v_fma_f32 v129, -v117, v117, 1.0
	s_andn2_saveexec_b64 s[6:7], s[6:7]
	v_fmamk_f32 v119, v118, 0x3c088889, v148
	v_fmaak_f32 v119, v118, v119, 0x3e2aaaab
	v_fma_f32 v119, v118, v119, 0.5
	v_fma_f32 v119, v118, v119, 1.0
	v_mul_f32_e64 v129, v119, -v118
	s_or_b64 exec, exec, s[6:7]
	v_mul_f32_e32 v118, 0x3fb8aa3b, v130
	v_exp_f32_e32 v118, v118
	v_add_f32_e32 v119, v130, v130
	v_cmp_nlt_f32_e32 vcc, s79, v119
	s_and_saveexec_b64 s[6:7], vcc
	s_xor_b64 s[6:7], exec, s[6:7]
	v_fma_f32 v130, -v118, v118, 1.0
	s_andn2_saveexec_b64 s[6:7], s[6:7]
	v_fmamk_f32 v130, v119, 0x3c088889, v148
	v_fmaak_f32 v130, v119, v130, 0x3e2aaaab
	v_fma_f32 v130, v119, v130, 0.5
	v_fma_f32 v130, v119, v130, 1.0
	v_mul_f32_e64 v130, v130, -v119
	s_or_b64 exec, exec, s[6:7]
	v_mul_f32_e32 v119, 0x3fb8aa3b, v131
	v_exp_f32_e32 v119, v119
	v_add_f32_e32 v138, v131, v131
	v_cmp_nlt_f32_e32 vcc, s79, v138
	s_and_saveexec_b64 s[6:7], vcc
	s_xor_b64 s[6:7], exec, s[6:7]
	v_fma_f32 v131, -v119, v119, 1.0
	s_andn2_saveexec_b64 s[6:7], s[6:7]
	v_fmamk_f32 v131, v138, 0x3c088889, v148
	v_fmaak_f32 v131, v138, v131, 0x3e2aaaab
	v_fma_f32 v131, v138, v131, 0.5
	v_fma_f32 v131, v138, v131, 1.0
	v_mul_f32_e64 v131, v131, -v138
	s_or_b64 exec, exec, s[6:7]
	v_max_f32_e32 v128, v128, v128
	v_max_f32_e32 v128, 0, v128
	v_sqrt_f32_e32 v128, v128
	v_max_f32_e32 v129, v129, v129
	v_max_f32_e32 v129, 0, v129
	v_sqrt_f32_e32 v129, v129
	s_waitcnt lgkmcnt(1)
	v_mul_f32_e32 v120, v120, v128
	s_waitcnt lgkmcnt(0)
	v_mul_f32_e32 v120, v124, v120
	v_max_f32_e32 v124, v130, v130
	v_max_f32_e32 v128, v131, v131
	v_max_f32_e32 v124, 0, v124
	v_max_f32_e32 v128, 0, v128
	v_sqrt_f32_e32 v124, v124
	v_sqrt_f32_e32 v128, v128
	v_mul_f32_e32 v121, v121, v129
	v_mul_f32_e32 v121, v125, v121
	v_mul_f32_e32 v122, v122, v124
	v_mul_f32_e32 v123, v123, v128
	v_mul_f32_e32 v122, v126, v122
	v_mul_f32_e32 v123, v127, v123
	ds_write_b128 v137, v[116:119] offset:25600
	ds_write_b128 v137, v[120:123] offset:58368
	ds_read_b128 v[128:131], v135 offset:41984
	v_add_u32_e32 v137, 0xe400, v135
	ds_read_b128 v[120:123], v137 offset:16384
	ds_read_b128 v[124:127], v136
	s_waitcnt lgkmcnt(2)
	v_mul_f32_e32 v116, 0x3fb8aa3b, v128
	v_exp_f32_e32 v116, v116
	v_add_f32_e32 v117, v128, v128
	v_cmp_nlt_f32_e32 vcc, s79, v117
	s_and_saveexec_b64 s[6:7], vcc
	s_xor_b64 s[6:7], exec, s[6:7]
	v_fma_f32 v128, -v116, v116, 1.0
	s_andn2_saveexec_b64 s[6:7], s[6:7]
	v_fmamk_f32 v118, v117, 0x3c088889, v148
	v_fmaak_f32 v118, v117, v118, 0x3e2aaaab
	v_fma_f32 v118, v117, v118, 0.5
	v_fma_f32 v118, v117, v118, 1.0
	v_mul_f32_e64 v128, v118, -v117
	s_or_b64 exec, exec, s[6:7]
	v_mul_f32_e32 v117, 0x3fb8aa3b, v129
	v_exp_f32_e32 v117, v117
	v_add_f32_e32 v118, v129, v129
	v_cmp_nlt_f32_e32 vcc, s79, v118
	s_and_saveexec_b64 s[6:7], vcc
	s_xor_b64 s[6:7], exec, s[6:7]
	v_fma_f32 v129, -v117, v117, 1.0
	s_andn2_saveexec_b64 s[6:7], s[6:7]
	v_fmamk_f32 v119, v118, 0x3c088889, v148
	v_fmaak_f32 v119, v118, v119, 0x3e2aaaab
	v_fma_f32 v119, v118, v119, 0.5
	v_fma_f32 v119, v118, v119, 1.0
	v_mul_f32_e64 v129, v119, -v118
	s_or_b64 exec, exec, s[6:7]
	v_mul_f32_e32 v118, 0x3fb8aa3b, v130
	v_exp_f32_e32 v118, v118
	v_add_f32_e32 v119, v130, v130
	v_cmp_nlt_f32_e32 vcc, s79, v119
	s_and_saveexec_b64 s[6:7], vcc
	s_xor_b64 s[6:7], exec, s[6:7]
	v_fma_f32 v130, -v118, v118, 1.0
	s_andn2_saveexec_b64 s[6:7], s[6:7]
	v_fmamk_f32 v130, v119, 0x3c088889, v148
	v_fmaak_f32 v130, v119, v130, 0x3e2aaaab
	v_fma_f32 v130, v119, v130, 0.5
	v_fma_f32 v130, v119, v130, 1.0
	v_mul_f32_e64 v130, v130, -v119
	s_or_b64 exec, exec, s[6:7]
	v_mul_f32_e32 v119, 0x3fb8aa3b, v131
	v_exp_f32_e32 v119, v119
	v_add_f32_e32 v136, v131, v131
	v_cmp_nlt_f32_e32 vcc, s79, v136
	s_and_saveexec_b64 s[6:7], vcc
	s_xor_b64 s[6:7], exec, s[6:7]
	v_fma_f32 v131, -v119, v119, 1.0
	s_andn2_saveexec_b64 s[6:7], s[6:7]
	v_fmamk_f32 v131, v136, 0x3c088889, v148
	v_fmaak_f32 v131, v136, v131, 0x3e2aaaab
	v_fma_f32 v131, v136, v131, 0.5
	v_fma_f32 v131, v136, v131, 1.0
	v_mul_f32_e64 v131, v131, -v136
	s_or_b64 exec, exec, s[6:7]
	v_max_f32_e32 v128, v128, v128
	v_max_f32_e32 v128, 0, v128
	v_sqrt_f32_e32 v128, v128
	v_max_f32_e32 v129, v129, v129
	v_max_f32_e32 v129, 0, v129
	v_sqrt_f32_e32 v129, v129
	s_waitcnt lgkmcnt(1)
	v_mul_f32_e32 v120, v120, v128
	s_waitcnt lgkmcnt(0)
	v_mul_f32_e32 v120, v124, v120
	v_max_f32_e32 v124, v130, v130
	v_max_f32_e32 v128, v131, v131
	v_max_f32_e32 v124, 0, v124
	v_max_f32_e32 v128, 0, v128
	v_sqrt_f32_e32 v124, v124
	v_sqrt_f32_e32 v128, v128
	v_mul_f32_e32 v121, v121, v129
	v_mul_f32_e32 v121, v125, v121
	v_mul_f32_e32 v122, v122, v124
	v_mul_f32_e32 v123, v123, v128
	v_mul_f32_e32 v122, v126, v122
	v_mul_f32_e32 v123, v127, v123
	ds_write_b128 v135, v[116:119] offset:41984
	ds_write_b128 v137, v[120:123] offset:16384
	v_add_u32_e32 v116, 0x1800, v133
	v_and_b32_e32 v117, 0x3ffff000, v116
	v_and_b32_e32 v116, 0xfc0, v116
	v_lshl_add_u32 v117, v117, 2, 0
	v_lshlrev_b32_e32 v116, 2, v116
	v_add3_u32 v132, v117, v116, v132
	v_xor_b32_e32 v132, v200, v132
	ds_read_b128 v[128:131], v132 offset:25600
	ds_read_b128 v[120:123], v132 offset:58368
	v_add_u32_e32 v116, v134, v116
	ds_read_b128 v[124:127], v116
	s_waitcnt lgkmcnt(2)
	v_mul_f32_e32 v116, 0x3fb8aa3b, v128
	v_exp_f32_e32 v116, v116
	v_add_f32_e32 v117, v128, v128
	v_cmp_nlt_f32_e32 vcc, s79, v117
	s_and_saveexec_b64 s[6:7], vcc
	s_xor_b64 s[6:7], exec, s[6:7]
	v_fma_f32 v128, -v116, v116, 1.0
	s_andn2_saveexec_b64 s[6:7], s[6:7]
	v_fmamk_f32 v118, v117, 0x3c088889, v148
	v_fmaak_f32 v118, v117, v118, 0x3e2aaaab
	v_fma_f32 v118, v117, v118, 0.5
	v_fma_f32 v118, v117, v118, 1.0
	v_mul_f32_e64 v128, v118, -v117
	s_or_b64 exec, exec, s[6:7]
	v_mul_f32_e32 v117, 0x3fb8aa3b, v129
	v_exp_f32_e32 v117, v117
	v_add_f32_e32 v118, v129, v129
	v_cmp_nlt_f32_e32 vcc, s79, v118
	s_and_saveexec_b64 s[6:7], vcc
	s_xor_b64 s[6:7], exec, s[6:7]
	v_fma_f32 v129, -v117, v117, 1.0
	s_andn2_saveexec_b64 s[6:7], s[6:7]
	v_fmamk_f32 v119, v118, 0x3c088889, v148
	v_fmaak_f32 v119, v118, v119, 0x3e2aaaab
	v_fma_f32 v119, v118, v119, 0.5
	v_fma_f32 v119, v118, v119, 1.0
	v_mul_f32_e64 v129, v119, -v118
	s_or_b64 exec, exec, s[6:7]
	v_mul_f32_e32 v118, 0x3fb8aa3b, v130
	v_exp_f32_e32 v118, v118
	v_add_f32_e32 v119, v130, v130
	v_cmp_nlt_f32_e32 vcc, s79, v119
	s_and_saveexec_b64 s[6:7], vcc
	s_xor_b64 s[6:7], exec, s[6:7]
	v_fma_f32 v130, -v118, v118, 1.0
	s_andn2_saveexec_b64 s[6:7], s[6:7]
	v_fmamk_f32 v130, v119, 0x3c088889, v148
	v_fmaak_f32 v130, v119, v130, 0x3e2aaaab
	v_fma_f32 v130, v119, v130, 0.5
	v_fma_f32 v130, v119, v130, 1.0
	v_mul_f32_e64 v130, v130, -v119
	s_or_b64 exec, exec, s[6:7]
	v_mul_f32_e32 v119, 0x3fb8aa3b, v131
	v_exp_f32_e32 v119, v119
	v_add_f32_e32 v133, v131, v131
	v_cmp_nlt_f32_e32 vcc, s79, v133
	s_and_saveexec_b64 s[6:7], vcc
	s_xor_b64 s[6:7], exec, s[6:7]
	v_fma_f32 v131, -v119, v119, 1.0
	s_andn2_saveexec_b64 s[6:7], s[6:7]
	v_fmamk_f32 v131, v133, 0x3c088889, v148
	v_fmaak_f32 v131, v133, v131, 0x3e2aaaab
	v_fma_f32 v131, v133, v131, 0.5
	v_fma_f32 v131, v133, v131, 1.0
	v_mul_f32_e64 v131, v131, -v133
	s_or_b64 exec, exec, s[6:7]
	v_max_f32_e32 v128, v128, v128
	v_max_f32_e32 v128, 0, v128
	v_sqrt_f32_e32 v128, v128
	v_max_f32_e32 v129, v129, v129
	v_max_f32_e32 v129, 0, v129
	v_sqrt_f32_e32 v129, v129
	s_waitcnt lgkmcnt(1)
	v_mul_f32_e32 v120, v120, v128
	v_max_f32_e32 v128, v130, v130
	s_waitcnt lgkmcnt(0)
	v_mul_f32_e32 v120, v124, v120
	v_max_f32_e32 v124, v131, v131
	v_max_f32_e32 v128, 0, v128
	v_max_f32_e32 v124, 0, v124
	v_sqrt_f32_e32 v128, v128
	v_sqrt_f32_e32 v124, v124
	v_ashrrev_i32_e32 v156, 7, v152
	v_mul_f32_e32 v121, v121, v129
	v_mul_f32_e32 v122, v122, v128
	v_and_b32_e32 v172, 0x7f, v152
	v_mul_f32_e32 v123, v123, v124
	v_lshlrev_b32_e32 v146, 4, v156
	v_mul_f32_e32 v121, v125, v121
	v_mul_f32_e32 v122, v126, v122
	v_bfe_u32 v153, v152, 6, 1
	v_mul_f32_e32 v123, v127, v123
	ds_write_b128 v132, v[116:119] offset:25600
	ds_write_b128 v132, v[120:123] offset:58368
	v_and_b32_e32 v154, 63, v152
	v_sub_u32_e32 v116, 63, v146
	v_cmp_gt_u32_e32 vcc, 64, v172
	v_or_b32_e32 v118, 1, v146

	s_nop 0
	v_cndmask_b32_e32 v155, v116, v146, vcc
	v_sub_u32_e32 v119, 63, v118
	v_or_b32_e32 v120, 2, v146

	v_cndmask_b32_e32 v157, v119, v118, vcc
	v_sub_u32_e32 v121, 63, v120
	v_or_b32_e32 v122, 3, v146


	v_cndmask_b32_e32 v158, v121, v120, vcc
	v_sub_u32_e32 v123, 63, v122
	v_or_b32_e32 v124, 4, v146
	s_waitcnt lgkmcnt(0)
	s_barrier
	ds_read2st64_b32 v[116:117], v176 offset0:100 offset1:228


	v_cndmask_b32_e32 v159, v123, v122, vcc
	v_sub_u32_e32 v125, 63, v124
	v_or_b32_e32 v126, 5, v146
	ds_read2st64_b32 v[118:119], v177 offset0:100 offset1:228


	v_cndmask_b32_e32 v160, v125, v124, vcc
	v_sub_u32_e32 v127, 63, v126
	v_or_b32_e32 v128, 6, v146
	ds_read2st64_b32 v[120:121], v178 offset0:100 offset1:228


	v_cndmask_b32_e32 v161, v127, v126, vcc
	v_sub_u32_e32 v129, 63, v128
	v_or_b32_e32 v130, 7, v146
	ds_read2st64_b32 v[122:123], v179 offset0:100 offset1:228


	v_cndmask_b32_e32 v162, v129, v128, vcc
	v_sub_u32_e32 v131, 63, v130
	v_or_b32_e32 v132, 8, v146
	ds_read2st64_b32 v[124:125], v180 offset0:100 offset1:228


	v_cndmask_b32_e32 v163, v131, v130, vcc
	v_sub_u32_e32 v133, 63, v132
	v_or_b32_e32 v134, 9, v146
	ds_read2st64_b32 v[126:127], v181 offset0:100 offset1:228


	v_cndmask_b32_e32 v164, v133, v132, vcc
	v_sub_u32_e32 v135, 63, v134
	v_or_b32_e32 v136, 10, v146
	s_waitcnt lgkmcnt(5)
	v_fma_f32 v173, 0, v116, v117
	ds_read2st64_b32 v[128:129], v182 offset0:100 offset1:228


	v_cndmask_b32_e32 v165, v135, v134, vcc
	v_sub_u32_e32 v137, 63, v136
	v_or_b32_e32 v138, 11, v146
	s_waitcnt lgkmcnt(5)
	v_fma_f32 v173, v173, v118, v119
	ds_read2st64_b32 v[130:131], v183 offset0:100 offset1:228


	v_cndmask_b32_e32 v166, v137, v136, vcc
	v_sub_u32_e32 v139, 63, v138
	v_or_b32_e32 v140, 12, v146
	v_mul_f32_e32 v174, v116, v118
	s_waitcnt lgkmcnt(5)
	v_fma_f32 v173, v173, v120, v121
	ds_read2st64_b32 v[132:133], v184 offset0:100 offset1:228


	v_cndmask_b32_e32 v167, v139, v138, vcc
	v_sub_u32_e32 v141, 63, v140
	v_or_b32_e32 v142, 13, v146
	v_mul_f32_e32 v174, v174, v120
	s_waitcnt lgkmcnt(5)
	v_fma_f32 v173, v173, v122, v123
	ds_read2st64_b32 v[134:135], v185 offset0:100 offset1:228


	v_cndmask_b32_e32 v168, v141, v140, vcc
	v_sub_u32_e32 v143, 63, v142
	v_or_b32_e32 v144, 14, v146
	v_mul_f32_e32 v174, v174, v122
	s_waitcnt lgkmcnt(5)
	v_fma_f32 v173, v173, v124, v125
	ds_read2st64_b32 v[136:137], v186 offset0:100 offset1:228


	v_cndmask_b32_e32 v169, v143, v142, vcc
	v_sub_u32_e32 v145, 63, v144
	v_or_b32_e32 v146, 15, v146
	v_mul_f32_e32 v174, v174, v124
	s_waitcnt lgkmcnt(5)
	v_fma_f32 v173, v173, v126, v127
	ds_read2st64_b32 v[138:139], v187 offset0:100 offset1:228


	v_cndmask_b32_e32 v170, v145, v144, vcc
	v_sub_u32_e32 v171, 63, v146
	v_mul_f32_e32 v174, v174, v126
	s_waitcnt lgkmcnt(5)
	v_fma_f32 v173, v173, v128, v129
	ds_read2st64_b32 v[140:141], v188 offset0:100 offset1:228


	v_cndmask_b32_e32 v171, v171, v146, vcc
	v_mul_f32_e32 v174, v174, v128
	s_waitcnt lgkmcnt(5)
	v_fma_f32 v173, v173, v130, v131
	ds_read2st64_b32 v[142:143], v189 offset0:100 offset1:228


	v_mul_f32_e32 v174, v174, v130
	s_waitcnt lgkmcnt(5)
	v_fma_f32 v173, v173, v132, v133
	ds_read2st64_b32 v[144:145], v190 offset0:100 offset1:228

	v_mul_f32_e32 v174, v174, v132
	s_waitcnt lgkmcnt(5)
	v_fma_f32 v173, v173, v134, v135
	ds_read2st64_b32 v[146:147], v191 offset0:100 offset1:228
	v_mul_f32_e32 v174, v174, v134
	s_waitcnt lgkmcnt(5)
	v_fma_f32 v173, v173, v136, v137
	v_mul_f32_e32 v174, v174, v136
	s_waitcnt lgkmcnt(4)
	v_fma_f32 v173, v173, v138, v139
	v_mul_f32_e32 v174, v174, v138
	s_waitcnt lgkmcnt(3)
	v_fma_f32 v173, v173, v140, v141
	v_mul_f32_e32 v174, v174, v140
	s_waitcnt lgkmcnt(2)
	v_fma_f32 v173, v173, v142, v143
	v_mul_f32_e32 v174, v174, v142
	s_waitcnt lgkmcnt(1)
	v_fma_f32 v173, v173, v144, v145
	v_lshl_add_u32 v152, v152, 2, 0
	v_mul_f32_e32 v174, v174, v144
	s_waitcnt lgkmcnt(0)
	v_fma_f32 v173, v173, v146, v147
	v_add_u32_e32 v175, 0x16400, v152
	v_add_u32_e32 v152, 0x16c00, v152
	v_mul_f32_e32 v174, v174, v146
	ds_write_b32 v152, v173
	v_cmp_lt_i32_e32 vcc, 0, v156
	v_lshl_add_u32 v172, v172, 2, 0
	v_mov_b32_e32 v152, v150
	ds_write_b32 v175, v174
	s_waitcnt lgkmcnt(0)
	s_barrier
	s_and_saveexec_b64 s[6:7], vcc
	s_cbranch_execnz .LBB0_774
	s_or_b64 exec, exec, s[6:7]
	v_cmp_lt_i32_e32 vcc, 1, v156
	s_and_saveexec_b64 s[6:7], vcc
	s_cbranch_execnz .LBB0_775
